# v18 + residual/softmax epilogue cross-lane sums via v_permlane16/32_swap (no LDS round trips) + KV epilogue row-scale loads hoisted (one wait, not eight)
# baseline (speedup 1.0000x reference)
; #define LAS __attribute__((address_space(3)))
; __device__ __forceinline__ unsigned cvt_pk_bf16(float lo, float hi) { unsigned r; asm volatile("v_cvt_pk_bf16_f32 %0, %1, %2" : "=v"(r) : "v"(lo), "v"(hi)); return r; }
;     __device__ __forceinline__ void operator()(Acc& acc, const Unit& u, int wr, int wc, int fr, int fq, LAS unsigned char*, const LAS float* rst) const {
;         const int l = u.pn >> 3, isV = (u.pn >> 2) & 1, h = u.pn & 3;
;         const int row0 = u.pm * 256 + wr * 64 + fr, cc0 = h * 256 + wc * 32 + 4 * fq;
;         float* dst = (isV ? dV : dK) + (size_t)l * 2048 * 1024;
; #pragma unroll
;         for (int ai = 0; ai < 2; ++ai)
; #pragma unroll
;             for (int m = 0; m < 4; ++m) {
;                 const int row = row0 + ai * 128 + m * 16; const float rs = rsm[row];
; #pragma unroll
;                 for (int bj = 0; bj < 2; ++bj)
; #pragma unroll
;                     for (int n = 0; n < 2; ++n) { const f32x4 v = acc[ai][bj][m][n] * rs; const int cc = cc0 + bj * 128 + n * 16;
;                         *(f32x4*)(dst + (size_t)row * 1024 + cc) = v;
;                         if (!isV) { u32x2 w; w.x = cvt_pk_bf16(v[0], v[1]); w.y = cvt_pk_bf16(v[2], v[3]); *(u32x2*)(Kb + ((size_t)l * 2048 + row) * 1024 + cc) = w; }
;                         else { u32x2 w; w.x = cvt_pk_bf16(v[0], v[1]); w.y = cvt_pk_bf16(v[2], v[3]); *(u32x2*)(Vt + ((size_t)l * 2048 + row) * 1024 + cc) = w; } }
.LBB0_202:
	v_lshl_add_u32 v138, s10, 8, v149
	v_ashrrev_i32_e32 v139, 31, v138
	v_lshl_add_u64 v[140:141], v[138:139], 2, s[6:7]
	global_load_dword v142, v[140:141], off
	global_load_dword v240, v[140:141], off offset:64
	global_load_dword v241, v[140:141], off offset:128
	global_load_dword v242, v[140:141], off offset:192
	global_load_dword v243, v[140:141], off offset:512
	global_load_dword v244, v[140:141], off offset:576
	global_load_dword v245, v[140:141], off offset:640
	global_load_dword v246, v[140:141], off offset:704
	s_lshl_b32 s1, s0, 8
	s_ashr_i32 s22, s0, 3
	s_and_b32 s20, s0, 4
	s_and_b32 s1, s1, 0x300
	s_bitcmp1_b32 s0, 2
	s_cselect_b64 s[10:11], -1, 0
	s_cmp_eq_u32 s20, 0
	s_cselect_b32 s0, s44, 0x9100000
	s_add_u32 s20, s48, s0
	s_addc_u32 s21, s49, 0
	s_ashr_i32 s23, s22, 31
	v_or_b32_e32 v155, s1, v151
	s_lshl_b64 s[0:1], s[22:23], 23
	s_add_u32 s20, s20, s0
	v_lshlrev_b64 v[144:145], 12, v[138:139]
	s_addc_u32 s21, s21, s1
	v_lshlrev_b32_e32 v132, 2, v155
	v_lshl_add_u64 v[144:145], s[20:21], 0, v[144:145]
	s_mov_b64 s[24:25], -1
	s_and_b64 vcc, exec, s[10:11]
	v_lshl_add_u64 v[144:145], v[144:145], 0, v[132:133]
	s_waitcnt vmcnt(0)
	v_pk_mul_f32 v[126:127], v[126:127], v[142:143] op_sel_hi:[1,0]
	v_pk_mul_f32 v[124:125], v[124:125], v[142:143] op_sel_hi:[1,0]
	global_store_dwordx4 v[144:145], v[124:127], off
	s_cbranch_vccz .LBB0_204
	v_cvt_pk_bf16_f32 v146, v124, v125
	v_cvt_pk_bf16_f32 v147, v126, v127
	s_mov_b64 s[24:25], 0

; __device__ __forceinline__ unsigned cvt_pk_bf16(float lo, float hi) { unsigned r; asm volatile("v_cvt_pk_bf16_f32 %0, %1, %2" : "=v"(r) : "v"(lo), "v"(hi)); return r; }
;     __device__ __forceinline__ void operator()(Acc& acc, const Unit& u, int wr, int wc, int fr, int fq, LAS unsigned char*, const LAS float* rst) const {
;     ...
;             for (int m = 0; m < 4; ++m) {
;                 const int row = row0 + ai * 128 + m * 16; const float rs = rsm[row];
; #pragma unroll
;                 for (int bj = 0; bj < 2; ++bj)
; #pragma unroll
;                     for (int n = 0; n < 2; ++n) { const f32x4 v = acc[ai][bj][m][n] * rs; const int cc = cc0 + bj * 128 + n * 16;
;                         *(f32x4*)(dst + (size_t)row * 1024 + cc) = v;
;                         if (!isV) { u32x2 w; w.x = cvt_pk_bf16(v[0], v[1]); w.y = cvt_pk_bf16(v[2], v[3]); *(u32x2*)(Kb + ((size_t)l * 2048 + row) * 1024 + cc) = w; }
;                         else { u32x2 w; w.x = cvt_pk_bf16(v[0], v[1]); w.y = cvt_pk_bf16(v[2], v[3]); *(u32x2*)(Vt + ((size_t)l * 2048 + row) * 1024 + cc) = w; } }
.LBB0_218:
	s_add_u32 s10, s50, s10
	s_addc_u32 s11, s51, s11
	v_lshl_add_u64 v[112:113], s[10:11], 0, v[126:127]
	v_mov_b32_e32 v125, v133
	v_lshl_add_u64 v[112:113], v[112:113], 0, v[124:125]
	global_store_dwordx2 v[112:113], v[116:117], off offset:288
	v_or_b32_e32 v116, 16, v138
	v_ashrrev_i32_e32 v117, 31, v116
	v_lshl_add_u64 v[112:113], v[116:117], 2, s[6:7]
	v_mov_b32_e32 v112, v240
	v_lshlrev_b64 v[114:115], 12, v[116:117]
	v_lshl_add_u64 v[114:115], s[20:21], 0, v[114:115]
	s_and_b64 vcc, exec, s[0:1]
	v_lshl_add_u64 v[114:115], v[114:115], 0, v[132:133]
	s_mov_b64 s[10:11], -1
	s_nop 0
	v_pk_mul_f32 v[110:111], v[110:111], v[112:113] op_sel_hi:[1,0]
	v_pk_mul_f32 v[108:109], v[108:109], v[112:113] op_sel_hi:[1,0]
	global_store_dwordx4 v[114:115], v[108:111], off
	s_cbranch_vccnz .LBB0_220
	s_mov_b64 s[10:11], 0
	v_cvt_pk_bf16_f32 v118, v108, v109
	v_cvt_pk_bf16_f32 v119, v110, v111

; __device__ __forceinline__ unsigned cvt_pk_bf16(float lo, float hi) { unsigned r; asm volatile("v_cvt_pk_bf16_f32 %0, %1, %2" : "=v"(r) : "v"(lo), "v"(hi)); return r; }
;     __device__ __forceinline__ void operator()(Acc& acc, const Unit& u, int wr, int wc, int fr, int fq, LAS unsigned char*, const LAS float* rst) const {
;     ...
;             for (int m = 0; m < 4; ++m) {
;                 const int row = row0 + ai * 128 + m * 16; const float rs = rsm[row];
; #pragma unroll
;                 for (int bj = 0; bj < 2; ++bj)
; #pragma unroll
;                     for (int n = 0; n < 2; ++n) { const f32x4 v = acc[ai][bj][m][n] * rs; const int cc = cc0 + bj * 128 + n * 16;
;                         *(f32x4*)(dst + (size_t)row * 1024 + cc) = v;
;                         if (!isV) { u32x2 w; w.x = cvt_pk_bf16(v[0], v[1]); w.y = cvt_pk_bf16(v[2], v[3]); *(u32x2*)(Kb + ((size_t)l * 2048 + row) * 1024 + cc) = w; }
;                         else { u32x2 w; w.x = cvt_pk_bf16(v[0], v[1]); w.y = cvt_pk_bf16(v[2], v[3]); *(u32x2*)(Vt + ((size_t)l * 2048 + row) * 1024 + cc) = w; } }
.LBB0_234:
	s_add_u32 s10, s50, s10
	s_addc_u32 s11, s51, s11
	v_lshl_add_u64 v[96:97], s[10:11], 0, v[108:109]
	v_mov_b32_e32 v125, v133
	v_lshl_add_u64 v[96:97], v[96:97], 0, v[124:125]
	global_store_dwordx2 v[96:97], v[100:101], off offset:288
	v_or_b32_e32 v100, 32, v138
	v_ashrrev_i32_e32 v101, 31, v100
	v_lshl_add_u64 v[96:97], v[100:101], 2, s[6:7]
	v_mov_b32_e32 v96, v241
	v_lshlrev_b64 v[98:99], 12, v[100:101]
	v_lshl_add_u64 v[98:99], s[20:21], 0, v[98:99]
	s_and_b64 vcc, exec, s[0:1]
	v_lshl_add_u64 v[98:99], v[98:99], 0, v[132:133]
	s_mov_b64 s[10:11], -1
	s_nop 0
	v_pk_mul_f32 v[94:95], v[94:95], v[96:97] op_sel_hi:[1,0]
	v_pk_mul_f32 v[92:93], v[92:93], v[96:97] op_sel_hi:[1,0]
	global_store_dwordx4 v[98:99], v[92:95], off
	s_cbranch_vccnz .LBB0_236
	s_mov_b64 s[10:11], 0
	v_cvt_pk_bf16_f32 v102, v92, v93
	v_cvt_pk_bf16_f32 v103, v94, v95

; __device__ __forceinline__ unsigned cvt_pk_bf16(float lo, float hi) { unsigned r; asm volatile("v_cvt_pk_bf16_f32 %0, %1, %2" : "=v"(r) : "v"(lo), "v"(hi)); return r; }
;     __device__ __forceinline__ void operator()(Acc& acc, const Unit& u, int wr, int wc, int fr, int fq, LAS unsigned char*, const LAS float* rst) const {
;     ...
;             for (int m = 0; m < 4; ++m) {
;                 const int row = row0 + ai * 128 + m * 16; const float rs = rsm[row];
; #pragma unroll
;                 for (int bj = 0; bj < 2; ++bj)
; #pragma unroll
;                     for (int n = 0; n < 2; ++n) { const f32x4 v = acc[ai][bj][m][n] * rs; const int cc = cc0 + bj * 128 + n * 16;
;                         *(f32x4*)(dst + (size_t)row * 1024 + cc) = v;
;                         if (!isV) { u32x2 w; w.x = cvt_pk_bf16(v[0], v[1]); w.y = cvt_pk_bf16(v[2], v[3]); *(u32x2*)(Kb + ((size_t)l * 2048 + row) * 1024 + cc) = w; }
;                         else { u32x2 w; w.x = cvt_pk_bf16(v[0], v[1]); w.y = cvt_pk_bf16(v[2], v[3]); *(u32x2*)(Vt + ((size_t)l * 2048 + row) * 1024 + cc) = w; } }
.LBB0_250:
	s_add_u32 s10, s50, s10
	s_addc_u32 s11, s51, s11
	v_lshl_add_u64 v[80:81], s[10:11], 0, v[92:93]
	v_mov_b32_e32 v125, v133
	v_lshl_add_u64 v[80:81], v[80:81], 0, v[124:125]
	global_store_dwordx2 v[80:81], v[84:85], off offset:288
	v_or_b32_e32 v84, 48, v138
	v_ashrrev_i32_e32 v85, 31, v84
	v_lshl_add_u64 v[80:81], v[84:85], 2, s[6:7]
	v_mov_b32_e32 v80, v242
	v_lshlrev_b64 v[82:83], 12, v[84:85]
	v_lshl_add_u64 v[82:83], s[20:21], 0, v[82:83]
	s_and_b64 vcc, exec, s[0:1]
	v_lshl_add_u64 v[82:83], v[82:83], 0, v[132:133]
	s_mov_b64 s[10:11], -1
	s_nop 0
	v_pk_mul_f32 v[78:79], v[78:79], v[80:81] op_sel_hi:[1,0]
	v_pk_mul_f32 v[76:77], v[76:77], v[80:81] op_sel_hi:[1,0]
	global_store_dwordx4 v[82:83], v[76:79], off
	s_cbranch_vccnz .LBB0_252
	s_mov_b64 s[10:11], 0
	v_cvt_pk_bf16_f32 v86, v76, v77
	v_cvt_pk_bf16_f32 v87, v78, v79

; __device__ __forceinline__ unsigned cvt_pk_bf16(float lo, float hi) { unsigned r; asm volatile("v_cvt_pk_bf16_f32 %0, %1, %2" : "=v"(r) : "v"(lo), "v"(hi)); return r; }
;     __device__ __forceinline__ void operator()(Acc& acc, const Unit& u, int wr, int wc, int fr, int fq, LAS unsigned char*, const LAS float* rst) const {
;     ...
;             for (int m = 0; m < 4; ++m) {
;                 const int row = row0 + ai * 128 + m * 16; const float rs = rsm[row];
; #pragma unroll
;                 for (int bj = 0; bj < 2; ++bj)
; #pragma unroll
;                     for (int n = 0; n < 2; ++n) { const f32x4 v = acc[ai][bj][m][n] * rs; const int cc = cc0 + bj * 128 + n * 16;
;                         *(f32x4*)(dst + (size_t)row * 1024 + cc) = v;
;                         if (!isV) { u32x2 w; w.x = cvt_pk_bf16(v[0], v[1]); w.y = cvt_pk_bf16(v[2], v[3]); *(u32x2*)(Kb + ((size_t)l * 2048 + row) * 1024 + cc) = w; }
;                         else { u32x2 w; w.x = cvt_pk_bf16(v[0], v[1]); w.y = cvt_pk_bf16(v[2], v[3]); *(u32x2*)(Vt + ((size_t)l * 2048 + row) * 1024 + cc) = w; } }
.LBB0_266:
	s_add_u32 s10, s50, s10
	s_addc_u32 s11, s51, s11
	v_lshl_add_u64 v[64:65], s[10:11], 0, v[76:77]
	v_mov_b32_e32 v125, v133
	v_lshl_add_u64 v[64:65], v[64:65], 0, v[124:125]
	global_store_dwordx2 v[64:65], v[68:69], off offset:288
	v_mov_b32_e32 v64, v243
	v_add_u32_e32 v68, 0x80, v138
	v_ashrrev_i32_e32 v69, 31, v68
	v_lshlrev_b64 v[66:67], 12, v[68:69]
	v_lshl_add_u64 v[66:67], s[20:21], 0, v[66:67]
	s_and_b64 vcc, exec, s[0:1]
	v_lshl_add_u64 v[66:67], v[66:67], 0, v[132:133]
	s_mov_b64 s[10:11], -1
	s_nop 0
	v_pk_mul_f32 v[62:63], v[62:63], v[64:65] op_sel_hi:[1,0]
	v_pk_mul_f32 v[60:61], v[60:61], v[64:65] op_sel_hi:[1,0]
	global_store_dwordx4 v[66:67], v[60:63], off
	s_cbranch_vccnz .LBB0_268
	s_mov_b64 s[10:11], 0
	v_cvt_pk_bf16_f32 v70, v60, v61
	v_cvt_pk_bf16_f32 v71, v62, v63

; __device__ __forceinline__ unsigned cvt_pk_bf16(float lo, float hi) { unsigned r; asm volatile("v_cvt_pk_bf16_f32 %0, %1, %2" : "=v"(r) : "v"(lo), "v"(hi)); return r; }
;     __device__ __forceinline__ void operator()(Acc& acc, const Unit& u, int wr, int wc, int fr, int fq, LAS unsigned char*, const LAS float* rst) const {
;     ...
;             for (int m = 0; m < 4; ++m) {
;                 const int row = row0 + ai * 128 + m * 16; const float rs = rsm[row];
; #pragma unroll
;                 for (int bj = 0; bj < 2; ++bj)
; #pragma unroll
;                     for (int n = 0; n < 2; ++n) { const f32x4 v = acc[ai][bj][m][n] * rs; const int cc = cc0 + bj * 128 + n * 16;
;                         *(f32x4*)(dst + (size_t)row * 1024 + cc) = v;
;                         if (!isV) { u32x2 w; w.x = cvt_pk_bf16(v[0], v[1]); w.y = cvt_pk_bf16(v[2], v[3]); *(u32x2*)(Kb + ((size_t)l * 2048 + row) * 1024 + cc) = w; }
;                         else { u32x2 w; w.x = cvt_pk_bf16(v[0], v[1]); w.y = cvt_pk_bf16(v[2], v[3]); *(u32x2*)(Vt + ((size_t)l * 2048 + row) * 1024 + cc) = w; } }
.LBB0_282:
	s_add_u32 s10, s50, s10
	s_addc_u32 s11, s51, s11
	v_lshl_add_u64 v[48:49], s[10:11], 0, v[60:61]
	v_mov_b32_e32 v125, v133
	v_lshl_add_u64 v[48:49], v[48:49], 0, v[124:125]
	global_store_dwordx2 v[48:49], v[52:53], off offset:288
	v_mov_b32_e32 v48, v244
	v_add_u32_e32 v52, 0x90, v138
	v_ashrrev_i32_e32 v53, 31, v52
	v_lshlrev_b64 v[50:51], 12, v[52:53]
	v_lshl_add_u64 v[50:51], s[20:21], 0, v[50:51]
	s_and_b64 vcc, exec, s[0:1]
	v_lshl_add_u64 v[50:51], v[50:51], 0, v[132:133]
	s_mov_b64 s[10:11], -1
	s_nop 0
	v_pk_mul_f32 v[46:47], v[46:47], v[48:49] op_sel_hi:[1,0]
	v_pk_mul_f32 v[44:45], v[44:45], v[48:49] op_sel_hi:[1,0]
	global_store_dwordx4 v[50:51], v[44:47], off
	s_cbranch_vccnz .LBB0_284
	s_mov_b64 s[10:11], 0
	v_cvt_pk_bf16_f32 v54, v44, v45
	v_cvt_pk_bf16_f32 v55, v46, v47

; __device__ __forceinline__ unsigned cvt_pk_bf16(float lo, float hi) { unsigned r; asm volatile("v_cvt_pk_bf16_f32 %0, %1, %2" : "=v"(r) : "v"(lo), "v"(hi)); return r; }
;     __device__ __forceinline__ void operator()(Acc& acc, const Unit& u, int wr, int wc, int fr, int fq, LAS unsigned char*, const LAS float* rst) const {
;     ...
;             for (int m = 0; m < 4; ++m) {
;                 const int row = row0 + ai * 128 + m * 16; const float rs = rsm[row];
; #pragma unroll
;                 for (int bj = 0; bj < 2; ++bj)
; #pragma unroll
;                     for (int n = 0; n < 2; ++n) { const f32x4 v = acc[ai][bj][m][n] * rs; const int cc = cc0 + bj * 128 + n * 16;
;                         *(f32x4*)(dst + (size_t)row * 1024 + cc) = v;
;                         if (!isV) { u32x2 w; w.x = cvt_pk_bf16(v[0], v[1]); w.y = cvt_pk_bf16(v[2], v[3]); *(u32x2*)(Kb + ((size_t)l * 2048 + row) * 1024 + cc) = w; }
;                         else { u32x2 w; w.x = cvt_pk_bf16(v[0], v[1]); w.y = cvt_pk_bf16(v[2], v[3]); *(u32x2*)(Vt + ((size_t)l * 2048 + row) * 1024 + cc) = w; } }
.LBB0_298:
	s_add_u32 s10, s50, s10
	s_addc_u32 s11, s51, s11
	v_lshl_add_u64 v[32:33], s[10:11], 0, v[44:45]
	v_mov_b32_e32 v125, v133
	v_lshl_add_u64 v[32:33], v[32:33], 0, v[124:125]
	global_store_dwordx2 v[32:33], v[36:37], off offset:288
	v_mov_b32_e32 v32, v245
	v_add_u32_e32 v36, 0xa0, v138
	v_ashrrev_i32_e32 v37, 31, v36
	v_lshlrev_b64 v[34:35], 12, v[36:37]
	v_lshl_add_u64 v[34:35], s[20:21], 0, v[34:35]
	s_and_b64 vcc, exec, s[0:1]
	v_lshl_add_u64 v[34:35], v[34:35], 0, v[132:133]
	s_mov_b64 s[10:11], -1
	s_nop 0
	v_pk_mul_f32 v[30:31], v[30:31], v[32:33] op_sel_hi:[1,0]
	v_pk_mul_f32 v[28:29], v[28:29], v[32:33] op_sel_hi:[1,0]
	global_store_dwordx4 v[34:35], v[28:31], off
	s_cbranch_vccnz .LBB0_300
	s_mov_b64 s[10:11], 0
	v_cvt_pk_bf16_f32 v38, v28, v29
	v_cvt_pk_bf16_f32 v39, v30, v31

; __device__ __forceinline__ unsigned cvt_pk_bf16(float lo, float hi) { unsigned r; asm volatile("v_cvt_pk_bf16_f32 %0, %1, %2" : "=v"(r) : "v"(lo), "v"(hi)); return r; }
;     __device__ __forceinline__ void operator()(Acc& acc, const Unit& u, int wr, int wc, int fr, int fq, LAS unsigned char*, const LAS float* rst) const {
;     ...
;             for (int m = 0; m < 4; ++m) {
;                 const int row = row0 + ai * 128 + m * 16; const float rs = rsm[row];
; #pragma unroll
;                 for (int bj = 0; bj < 2; ++bj)
; #pragma unroll
;                     for (int n = 0; n < 2; ++n) { const f32x4 v = acc[ai][bj][m][n] * rs; const int cc = cc0 + bj * 128 + n * 16;
;                         *(f32x4*)(dst + (size_t)row * 1024 + cc) = v;
;                         if (!isV) { u32x2 w; w.x = cvt_pk_bf16(v[0], v[1]); w.y = cvt_pk_bf16(v[2], v[3]); *(u32x2*)(Kb + ((size_t)l * 2048 + row) * 1024 + cc) = w; }
;                         else { u32x2 w; w.x = cvt_pk_bf16(v[0], v[1]); w.y = cvt_pk_bf16(v[2], v[3]); *(u32x2*)(Vt + ((size_t)l * 2048 + row) * 1024 + cc) = w; } }
.LBB0_314:
	s_add_u32 s10, s50, s10
	s_addc_u32 s11, s51, s11
	v_lshl_add_u64 v[16:17], s[10:11], 0, v[28:29]
	v_mov_b32_e32 v125, v133
	v_lshl_add_u64 v[16:17], v[16:17], 0, v[124:125]
	global_store_dwordx2 v[16:17], v[20:21], off offset:288
	v_mov_b32_e32 v16, v246
	v_add_u32_e32 v20, 0xb0, v138
	v_ashrrev_i32_e32 v21, 31, v20
	v_lshlrev_b64 v[18:19], 12, v[20:21]
	v_lshl_add_u64 v[18:19], s[20:21], 0, v[18:19]
	s_and_b64 vcc, exec, s[0:1]
	v_lshl_add_u64 v[18:19], v[18:19], 0, v[132:133]
	s_mov_b64 s[10:11], -1
	s_nop 0
	v_pk_mul_f32 v[14:15], v[14:15], v[16:17] op_sel_hi:[1,0]
	v_pk_mul_f32 v[12:13], v[12:13], v[16:17] op_sel_hi:[1,0]
	global_store_dwordx4 v[18:19], v[12:15], off
	s_cbranch_vccnz .LBB0_316
	s_mov_b64 s[10:11], 0
	v_cvt_pk_bf16_f32 v22, v12, v13
	v_cvt_pk_bf16_f32 v23, v14, v15

;     __device__ __forceinline__ void operator()(Acc& acc, const Unit& u, int wr, int wc, int fr, int fq, LAS unsigned char* lds, const LAS float* rst) const {
;     ...
;                 float mx = -INFINITY;
; #pragma unroll
;                 for (int bj = 0; bj < 2; ++bj)
; #pragma unroll
;                     for (int n = 0; n < 2; ++n) { const f32x4 v = acc[ai][bj][m][n]; mx = fmaxf(mx, fmaxf(fmaxf(v[0], v[1]), fmaxf(v[2], v[3]))); }
;                 mx = fmaxf(mx, __shfl_xor(mx, 16)); mx = fmaxf(mx, __shfl_xor(mx, 32));
;                 float s = 0.f;
; #pragma unroll
;                 for (int bj = 0; bj < 2; ++bj)
; #pragma unroll
;                     for (int n = 0; n < 2; ++n) { f32x4 v = acc[ai][bj][m][n];
; #pragma unroll
;                         for (int j = 0; j < 4; ++j) v[j] = __builtin_amdgcn_exp2f(v[j] - mx);
;                         acc[ai][bj][m][n] = v; s += (v[0] + v[1]) + (v[2] + v[3]); }
;                 s += __shfl_xor(s, 16); s += __shfl_xor(s, 32);
;                 if (fq == 0) Xw[(ai * 128 + m * 16) * 4] = (f32x2){mx, s};
.LBB0_516:
	v_and_b32_e32 v137, 64, v185
	v_xor_b32_e32 v136, 16, v185
	v_add_u32_e32 v137, 64, v137
	v_cmp_lt_i32_e32 vcc, v136, v137
	v_max_f32_e32 v138, v128, v128
	v_max_f32_e32 v139, v120, v120
	v_cndmask_b32_e32 v136, v185, v136, vcc
	v_lshlrev_b32_e32 v154, 2, v136
	v_max_f32_e32 v136, v129, v129
	v_max_f32_e32 v136, v138, v136
	v_max_f32_e32 v138, v121, v121
	v_max_f32_e32 v138, v139, v138
	v_max3_f32 v136, v126, v127, v136
	v_max3_f32 v138, v118, v119, v138
	s_mov_b32 s18, 0xff800000
	v_max3_f32 v136, v136, s18, v138
	v_max_f32_e32 v138, v125, v125
	v_max_f32_e32 v139, v124, v124
	v_max_f32_e32 v138, v139, v138
	v_max_f32_e32 v139, v117, v117
	v_max_f32_e32 v140, v116, v116
	v_max_f32_e32 v139, v140, v139
	v_max3_f32 v138, v122, v123, v138
	v_max3_f32 v139, v114, v115, v139
	v_max3_f32 v136, v136, v138, v139
	v_mov_b32_e32 v138, v136
	s_nop 1
	v_permlane16_swap_b32 v136, v138
	v_xor_b32_e32 v139, 32, v185
	v_cmp_lt_i32_e32 vcc, v139, v137
	v_mov_b32_e32 v157, v152
	v_mov_b32_e32 v156, v151
	v_cndmask_b32_e32 v137, v185, v139, vcc
	v_lshlrev_b32_e32 v155, 2, v137
	s_waitcnt lgkmcnt(0)
	v_max_f32_e32 v137, v138, v138
	v_max_f32_e32 v136, v136, v137
	v_mov_b32_e32 v137, v136
	s_nop 1
	v_permlane32_swap_b32 v136, v137
	s_waitcnt lgkmcnt(0)
	v_max_f32_e32 v137, v137, v137
	v_max_f32_e32 v146, v136, v137
	v_sub_f32_e32 v126, v126, v146
	v_exp_f32_e32 v136, v126
	v_sub_f32_e32 v126, v127, v146
	v_exp_f32_e32 v137, v126
	v_sub_f32_e32 v126, v128, v146
	v_exp_f32_e32 v140, v126
	v_sub_f32_e32 v126, v129, v146
	v_exp_f32_e32 v141, v126
	v_sub_f32_e32 v118, v118, v146
	v_exp_f32_e32 v138, v118
	v_sub_f32_e32 v118, v119, v146
	v_exp_f32_e32 v139, v118
	v_sub_f32_e32 v118, v120, v146
	v_add_f32_e32 v126, v136, v137
	v_add_f32_e32 v127, v140, v141
	v_exp_f32_e32 v144, v118
	v_sub_f32_e32 v118, v121, v146
	v_sub_f32_e32 v121, v122, v146
	v_exp_f32_e32 v145, v118
	v_add_f32_e32 v118, v126, v127
	v_exp_f32_e32 v126, v121
	v_sub_f32_e32 v121, v123, v146
	v_sub_f32_e32 v114, v114, v146
	v_exp_f32_e32 v127, v121
	v_sub_f32_e32 v121, v124, v146
	v_exp_f32_e32 v128, v114
	v_sub_f32_e32 v114, v115, v146
	v_exp_f32_e32 v124, v121
	v_sub_f32_e32 v121, v125, v146
	v_exp_f32_e32 v129, v114
	v_sub_f32_e32 v114, v116, v146
	v_exp_f32_e32 v125, v121
	v_exp_f32_e32 v142, v114
	v_sub_f32_e32 v114, v117, v146
	v_exp_f32_e32 v143, v114
	v_add_f32_e32 v119, v138, v139
	v_add_f32_e32 v120, v144, v145
	v_add_f32_e32 v118, 0, v118
	v_add_f32_e32 v119, v119, v120
	v_add_f32_e32 v118, v119, v118
	v_add_f32_e32 v119, v126, v127
	v_add_f32_e32 v120, v124, v125
	v_add_f32_e32 v114, v119, v120
	v_add_f32_e32 v115, v128, v129
	v_add_f32_e32 v116, v142, v143
	v_add_f32_e32 v114, v114, v118
	v_add_f32_e32 v115, v115, v116
	v_add_f32_e32 v114, v115, v114
	v_mov_b32_e32 v115, v114
	s_nop 1
	v_permlane16_swap_b32 v114, v115
	s_waitcnt lgkmcnt(0)
	v_add_f32_e32 v114, v114, v115
	v_mov_b32_e32 v115, v114
	s_nop 1
	v_permlane32_swap_b32 v114, v115
	s_and_saveexec_b64 s[10:11], s[0:1]
	s_cbranch_execz .LBB0_518
	s_waitcnt lgkmcnt(0)
	v_add_f32_e32 v147, v114, v115
	v_add_u32_e32 v114, 0, v157
	ds_write_b64 v114, v[146:147]
.LBB0_518:
	s_or_b64 exec, exec, s[10:11]
	v_max_f32_e32 v114, v113, v113
	s_waitcnt lgkmcnt(0)
	v_max_f32_e32 v115, v112, v112
	v_max_f32_e32 v114, v115, v114
	v_max_f32_e32 v115, v105, v105
	v_max_f32_e32 v116, v104, v104
	v_max_f32_e32 v115, v116, v115
	v_max3_f32 v114, v110, v111, v114
	v_max3_f32 v115, v102, v103, v115
	v_max3_f32 v114, v114, s18, v115
	v_max_f32_e32 v115, v109, v109
	v_max_f32_e32 v116, v108, v108
	v_max_f32_e32 v115, v116, v115
	v_max_f32_e32 v116, v101, v101
	v_max_f32_e32 v117, v100, v100
	v_max_f32_e32 v116, v117, v116
	v_max3_f32 v115, v106, v107, v115
	v_max3_f32 v116, v98, v99, v116
	v_max3_f32 v114, v114, v115, v116
	v_mov_b32_e32 v115, v114
	s_nop 1
	v_permlane16_swap_b32 v114, v115
	s_waitcnt lgkmcnt(0)
	v_max_f32_e32 v115, v115, v115
	v_max_f32_e32 v114, v114, v115
	v_mov_b32_e32 v115, v114
	s_nop 1
	v_permlane32_swap_b32 v114, v115
	s_waitcnt lgkmcnt(0)
	v_max_f32_e32 v115, v115, v115
	v_max_f32_e32 v146, v114, v115
	v_sub_f32_e32 v110, v110, v146
	v_exp_f32_e32 v114, v110
	v_sub_f32_e32 v110, v111, v146
	v_exp_f32_e32 v115, v110
	v_sub_f32_e32 v110, v112, v146
	v_exp_f32_e32 v118, v110
	v_sub_f32_e32 v110, v113, v146
	v_exp_f32_e32 v119, v110
	v_sub_f32_e32 v102, v102, v146
	v_exp_f32_e32 v116, v102
	v_sub_f32_e32 v102, v103, v146
	v_exp_f32_e32 v117, v102
	v_sub_f32_e32 v102, v104, v146
	v_add_f32_e32 v110, v114, v115
	v_add_f32_e32 v111, v118, v119
	v_exp_f32_e32 v122, v102
	v_sub_f32_e32 v102, v105, v146
	v_sub_f32_e32 v105, v106, v146
	v_exp_f32_e32 v123, v102
	v_add_f32_e32 v102, v110, v111
	v_exp_f32_e32 v110, v105
	v_sub_f32_e32 v105, v107, v146
	v_sub_f32_e32 v98, v98, v146
	v_exp_f32_e32 v111, v105
	v_sub_f32_e32 v105, v108, v146
	v_exp_f32_e32 v112, v98
	v_sub_f32_e32 v98, v99, v146
	v_exp_f32_e32 v108, v105
	v_sub_f32_e32 v105, v109, v146
	v_exp_f32_e32 v113, v98
	v_sub_f32_e32 v98, v100, v146
	v_exp_f32_e32 v109, v105
	v_exp_f32_e32 v120, v98
	v_sub_f32_e32 v98, v101, v146
	v_exp_f32_e32 v121, v98
	v_add_f32_e32 v103, v116, v117
	v_add_f32_e32 v104, v122, v123
	v_add_f32_e32 v102, 0, v102
	v_add_f32_e32 v103, v103, v104
	v_add_f32_e32 v102, v103, v102
	v_add_f32_e32 v103, v110, v111
	v_add_f32_e32 v104, v108, v109
	v_add_f32_e32 v98, v103, v104
	v_add_f32_e32 v99, v112, v113
	v_add_f32_e32 v100, v120, v121
	v_add_f32_e32 v98, v98, v102
	v_add_f32_e32 v99, v99, v100
	v_add_f32_e32 v98, v99, v98
	v_mov_b32_e32 v99, v98
	s_nop 1
	v_permlane16_swap_b32 v98, v99
	s_waitcnt lgkmcnt(0)
	v_add_f32_e32 v98, v98, v99
	v_mov_b32_e32 v99, v98
	s_nop 1
	v_permlane32_swap_b32 v98, v99
	s_and_saveexec_b64 s[10:11], s[0:1]
	s_cbranch_execz .LBB0_520
	s_waitcnt lgkmcnt(0)
	v_add_f32_e32 v147, v98, v99
	v_add_u32_e32 v98, 0, v157
	ds_write_b64 v98, v[146:147] offset:512
;     __device__ __forceinline__ void operator()(Acc& acc, const Unit& u, int wr, int wc, int fr, int fq, LAS unsigned char* lds, const LAS float* rst) const {
;     ...
;                 float mx = -INFINITY;
; #pragma unroll
;                 for (int bj = 0; bj < 2; ++bj)
; #pragma unroll
;                     for (int n = 0; n < 2; ++n) { const f32x4 v = acc[ai][bj][m][n]; mx = fmaxf(mx, fmaxf(fmaxf(v[0], v[1]), fmaxf(v[2], v[3]))); }
;                 mx = fmaxf(mx, __shfl_xor(mx, 16)); mx = fmaxf(mx, __shfl_xor(mx, 32));
;                 float s = 0.f;
; #pragma unroll
;                 for (int bj = 0; bj < 2; ++bj)
; #pragma unroll
;                     for (int n = 0; n < 2; ++n) { f32x4 v = acc[ai][bj][m][n];
; #pragma unroll
;                         for (int j = 0; j < 4; ++j) v[j] = __builtin_amdgcn_exp2f(v[j] - mx);
;                         acc[ai][bj][m][n] = v; s += (v[0] + v[1]) + (v[2] + v[3]); }
;                 s += __shfl_xor(s, 16); s += __shfl_xor(s, 32);
;                 if (fq == 0) Xw[(ai * 128 + m * 16) * 4] = (f32x2){mx, s};
.LBB0_520:
	s_or_b64 exec, exec, s[10:11]
	v_max_f32_e32 v98, v97, v97
	s_waitcnt lgkmcnt(0)
	v_max_f32_e32 v99, v96, v96
	v_max_f32_e32 v98, v99, v98
	v_max_f32_e32 v99, v89, v89
	v_max_f32_e32 v100, v88, v88
	v_max_f32_e32 v99, v100, v99
	v_max3_f32 v98, v94, v95, v98
	v_max3_f32 v99, v86, v87, v99
	v_max3_f32 v98, v98, s18, v99
	v_max_f32_e32 v99, v93, v93
	v_max_f32_e32 v100, v92, v92
	v_max_f32_e32 v99, v100, v99
	v_max_f32_e32 v100, v85, v85
	v_max_f32_e32 v101, v84, v84
	v_max_f32_e32 v100, v101, v100
	v_max3_f32 v99, v90, v91, v99
	v_max3_f32 v100, v82, v83, v100
	v_max3_f32 v98, v98, v99, v100
	v_mov_b32_e32 v99, v98
	s_nop 1
	v_permlane16_swap_b32 v98, v99
	s_waitcnt lgkmcnt(0)
	v_max_f32_e32 v99, v99, v99
	v_max_f32_e32 v98, v98, v99
	v_mov_b32_e32 v99, v98
	s_nop 1
	v_permlane32_swap_b32 v98, v99
	s_waitcnt lgkmcnt(0)
	v_max_f32_e32 v99, v99, v99
	v_max_f32_e32 v146, v98, v99
	v_sub_f32_e32 v94, v94, v146
	v_exp_f32_e32 v98, v94
	v_sub_f32_e32 v94, v95, v146
	v_exp_f32_e32 v99, v94
	v_sub_f32_e32 v94, v96, v146
	v_exp_f32_e32 v102, v94
	v_sub_f32_e32 v94, v97, v146
	v_exp_f32_e32 v103, v94
	v_sub_f32_e32 v86, v86, v146
	v_exp_f32_e32 v100, v86
	v_sub_f32_e32 v86, v87, v146
	v_exp_f32_e32 v101, v86
	v_sub_f32_e32 v86, v88, v146
	v_add_f32_e32 v94, v98, v99
	v_add_f32_e32 v95, v102, v103
	v_exp_f32_e32 v106, v86
	v_sub_f32_e32 v86, v89, v146
	v_sub_f32_e32 v89, v90, v146
	v_exp_f32_e32 v107, v86
	v_add_f32_e32 v86, v94, v95
	v_exp_f32_e32 v94, v89
	v_sub_f32_e32 v89, v91, v146
	v_sub_f32_e32 v82, v82, v146
	v_exp_f32_e32 v95, v89
	v_sub_f32_e32 v89, v92, v146
	v_exp_f32_e32 v96, v82
	v_sub_f32_e32 v82, v83, v146
	v_exp_f32_e32 v92, v89
	v_sub_f32_e32 v89, v93, v146
	v_exp_f32_e32 v97, v82
	v_sub_f32_e32 v82, v84, v146
	v_exp_f32_e32 v93, v89
	v_exp_f32_e32 v104, v82
	v_sub_f32_e32 v82, v85, v146
	v_exp_f32_e32 v105, v82
	v_add_f32_e32 v87, v100, v101
	v_add_f32_e32 v88, v106, v107
	v_add_f32_e32 v86, 0, v86
	v_add_f32_e32 v87, v87, v88
	v_add_f32_e32 v86, v87, v86
	v_add_f32_e32 v87, v94, v95
	v_add_f32_e32 v88, v92, v93
	v_add_f32_e32 v82, v87, v88
	v_add_f32_e32 v83, v96, v97
	v_add_f32_e32 v84, v104, v105
	v_add_f32_e32 v82, v82, v86
	v_add_f32_e32 v83, v83, v84
	v_add_f32_e32 v82, v83, v82
	v_mov_b32_e32 v83, v82
	s_nop 1
	v_permlane16_swap_b32 v82, v83
	s_waitcnt lgkmcnt(0)
	v_add_f32_e32 v82, v82, v83
	v_mov_b32_e32 v83, v82
	s_nop 1
	v_permlane32_swap_b32 v82, v83
	s_and_saveexec_b64 s[10:11], s[0:1]
	s_cbranch_execz .LBB0_522
	s_waitcnt lgkmcnt(0)
	v_add_f32_e32 v147, v82, v83
	v_add_u32_e32 v82, 0, v157
	ds_write_b64 v82, v[146:147] offset:1024
.LBB0_522:
	s_or_b64 exec, exec, s[10:11]
	v_max_f32_e32 v82, v81, v81
	s_waitcnt lgkmcnt(0)
	v_max_f32_e32 v83, v80, v80
	v_max_f32_e32 v82, v83, v82
	v_max_f32_e32 v83, v73, v73
	v_max_f32_e32 v84, v72, v72
	v_max_f32_e32 v83, v84, v83
	v_max3_f32 v82, v78, v79, v82
	v_max3_f32 v83, v70, v71, v83
	v_max3_f32 v82, v82, s18, v83
	v_max_f32_e32 v83, v77, v77
	v_max_f32_e32 v84, v76, v76
	v_max_f32_e32 v83, v84, v83
	v_max_f32_e32 v84, v69, v69
	v_max_f32_e32 v85, v68, v68
	v_max_f32_e32 v84, v85, v84
	v_max3_f32 v83, v74, v75, v83
	v_max3_f32 v84, v66, v67, v84
	v_max3_f32 v82, v82, v83, v84
	v_mov_b32_e32 v83, v82
	s_nop 1
	v_permlane16_swap_b32 v82, v83
	s_waitcnt lgkmcnt(0)
	v_max_f32_e32 v83, v83, v83
	v_max_f32_e32 v82, v82, v83
	v_mov_b32_e32 v83, v82
	s_nop 1
	v_permlane32_swap_b32 v82, v83
	s_waitcnt lgkmcnt(0)
	v_max_f32_e32 v83, v83, v83
	v_max_f32_e32 v146, v82, v83
	v_sub_f32_e32 v78, v78, v146
	v_exp_f32_e32 v82, v78
	v_sub_f32_e32 v78, v79, v146
	v_exp_f32_e32 v83, v78
	v_sub_f32_e32 v78, v80, v146
	v_exp_f32_e32 v86, v78
	v_sub_f32_e32 v78, v81, v146
	v_exp_f32_e32 v87, v78
	v_sub_f32_e32 v70, v70, v146
	v_exp_f32_e32 v84, v70
	v_sub_f32_e32 v70, v71, v146
	v_exp_f32_e32 v85, v70
	v_sub_f32_e32 v70, v72, v146
	v_add_f32_e32 v78, v82, v83
	v_add_f32_e32 v79, v86, v87
	v_exp_f32_e32 v90, v70
	v_sub_f32_e32 v70, v73, v146
	v_sub_f32_e32 v73, v74, v146
	v_exp_f32_e32 v91, v70
	v_add_f32_e32 v70, v78, v79
	v_exp_f32_e32 v78, v73
	v_sub_f32_e32 v73, v75, v146
	v_sub_f32_e32 v66, v66, v146
	v_exp_f32_e32 v79, v73
	v_sub_f32_e32 v73, v76, v146
	v_exp_f32_e32 v80, v66
	v_sub_f32_e32 v66, v67, v146
	v_exp_f32_e32 v76, v73
	v_sub_f32_e32 v73, v77, v146
	v_exp_f32_e32 v81, v66
	v_sub_f32_e32 v66, v68, v146
	v_exp_f32_e32 v77, v73
	v_exp_f32_e32 v88, v66
	v_sub_f32_e32 v66, v69, v146
	v_exp_f32_e32 v89, v66
	v_add_f32_e32 v71, v84, v85
	v_add_f32_e32 v72, v90, v91
	v_add_f32_e32 v70, 0, v70
	v_add_f32_e32 v71, v71, v72
	v_add_f32_e32 v70, v71, v70
	v_add_f32_e32 v71, v78, v79
	v_add_f32_e32 v72, v76, v77
	v_add_f32_e32 v66, v71, v72
	v_add_f32_e32 v67, v80, v81
	v_add_f32_e32 v68, v88, v89
	v_add_f32_e32 v66, v66, v70
	v_add_f32_e32 v67, v67, v68
	v_add_f32_e32 v66, v67, v66
	v_mov_b32_e32 v67, v66
	s_nop 1
	v_permlane16_swap_b32 v66, v67
	s_waitcnt lgkmcnt(0)
	v_add_f32_e32 v66, v66, v67
	v_mov_b32_e32 v67, v66
	s_nop 1
	v_permlane32_swap_b32 v66, v67
	s_and_saveexec_b64 s[10:11], s[0:1]
	s_cbranch_execz .LBB0_524
	s_waitcnt lgkmcnt(0)
	v_add_f32_e32 v147, v66, v67
	v_add_u32_e32 v66, 0, v157
	ds_write_b64 v66, v[146:147] offset:1536
;     __device__ __forceinline__ void operator()(Acc& acc, const Unit& u, int wr, int wc, int fr, int fq, LAS unsigned char* lds, const LAS float* rst) const {
;     ...
;                 float mx = -INFINITY;
; #pragma unroll
;                 for (int bj = 0; bj < 2; ++bj)
; #pragma unroll
;                     for (int n = 0; n < 2; ++n) { const f32x4 v = acc[ai][bj][m][n]; mx = fmaxf(mx, fmaxf(fmaxf(v[0], v[1]), fmaxf(v[2], v[3]))); }
;                 mx = fmaxf(mx, __shfl_xor(mx, 16)); mx = fmaxf(mx, __shfl_xor(mx, 32));
;                 float s = 0.f;
; #pragma unroll
;                 for (int bj = 0; bj < 2; ++bj)
; #pragma unroll
;                     for (int n = 0; n < 2; ++n) { f32x4 v = acc[ai][bj][m][n];
; #pragma unroll
;                         for (int j = 0; j < 4; ++j) v[j] = __builtin_amdgcn_exp2f(v[j] - mx);
;                         acc[ai][bj][m][n] = v; s += (v[0] + v[1]) + (v[2] + v[3]); }
;                 s += __shfl_xor(s, 16); s += __shfl_xor(s, 32);
;                 if (fq == 0) Xw[(ai * 128 + m * 16) * 4] = (f32x2){mx, s};
.LBB0_524:
	s_or_b64 exec, exec, s[10:11]
	v_max_f32_e32 v66, v65, v65
	s_waitcnt lgkmcnt(0)
	v_max_f32_e32 v67, v64, v64
	v_max_f32_e32 v66, v67, v66
	v_max_f32_e32 v67, v57, v57
	v_max_f32_e32 v68, v56, v56
	v_max_f32_e32 v67, v68, v67
	v_max3_f32 v66, v62, v63, v66
	v_max3_f32 v67, v54, v55, v67
	v_max3_f32 v66, v66, s18, v67
	v_max_f32_e32 v67, v61, v61
	v_max_f32_e32 v68, v60, v60
	v_max_f32_e32 v67, v68, v67
	v_max_f32_e32 v68, v53, v53
	v_max_f32_e32 v69, v52, v52
	v_max_f32_e32 v68, v69, v68
	v_max3_f32 v67, v58, v59, v67
	v_max3_f32 v68, v50, v51, v68
	v_max3_f32 v66, v66, v67, v68
	v_mov_b32_e32 v67, v66
	s_nop 1
	v_permlane16_swap_b32 v66, v67
	s_waitcnt lgkmcnt(0)
	v_max_f32_e32 v67, v67, v67
	v_max_f32_e32 v66, v66, v67
	v_mov_b32_e32 v67, v66
	s_nop 1
	v_permlane32_swap_b32 v66, v67
	s_waitcnt lgkmcnt(0)
	v_max_f32_e32 v67, v67, v67
	v_max_f32_e32 v146, v66, v67
	v_sub_f32_e32 v62, v62, v146
	v_exp_f32_e32 v66, v62
	v_sub_f32_e32 v62, v63, v146
	v_exp_f32_e32 v67, v62
	v_sub_f32_e32 v62, v64, v146
	v_exp_f32_e32 v72, v62
	v_sub_f32_e32 v62, v65, v146
	v_exp_f32_e32 v73, v62
	v_sub_f32_e32 v54, v54, v146
	v_exp_f32_e32 v68, v54
	v_sub_f32_e32 v54, v55, v146
	v_exp_f32_e32 v69, v54
	v_sub_f32_e32 v54, v56, v146
	v_add_f32_e32 v62, v66, v67
	v_add_f32_e32 v63, v72, v73
	v_exp_f32_e32 v74, v54
	v_sub_f32_e32 v54, v57, v146
	v_sub_f32_e32 v57, v58, v146
	v_exp_f32_e32 v75, v54
	v_add_f32_e32 v54, v62, v63
	v_exp_f32_e32 v62, v57
	v_sub_f32_e32 v57, v59, v146
	v_sub_f32_e32 v50, v50, v146
	v_exp_f32_e32 v63, v57
	v_sub_f32_e32 v57, v60, v146
	v_exp_f32_e32 v64, v50
	v_sub_f32_e32 v50, v51, v146
	v_exp_f32_e32 v60, v57
	v_sub_f32_e32 v57, v61, v146
	v_exp_f32_e32 v65, v50
	v_sub_f32_e32 v50, v52, v146
	v_exp_f32_e32 v61, v57
	v_exp_f32_e32 v70, v50
	v_sub_f32_e32 v50, v53, v146
	v_exp_f32_e32 v71, v50
	v_add_f32_e32 v55, v68, v69
	v_add_f32_e32 v56, v74, v75
	v_add_f32_e32 v54, 0, v54
	v_add_f32_e32 v55, v55, v56
	v_add_f32_e32 v54, v55, v54
	v_add_f32_e32 v55, v62, v63
	v_add_f32_e32 v56, v60, v61
	v_add_f32_e32 v50, v55, v56
	v_add_f32_e32 v51, v64, v65
	v_add_f32_e32 v52, v70, v71
	v_add_f32_e32 v50, v50, v54
	v_add_f32_e32 v51, v51, v52
	v_add_f32_e32 v50, v51, v50
	v_mov_b32_e32 v51, v50
	s_nop 1
	v_permlane16_swap_b32 v50, v51
	s_waitcnt lgkmcnt(0)
	v_add_f32_e32 v50, v50, v51
	v_mov_b32_e32 v51, v50
	s_nop 1
	v_permlane32_swap_b32 v50, v51
	s_and_saveexec_b64 s[10:11], s[0:1]
	s_cbranch_execz .LBB0_526
	s_waitcnt lgkmcnt(0)
	v_add_f32_e32 v147, v50, v51
	v_add_u32_e32 v50, 0, v157
	ds_write_b64 v50, v[146:147] offset:4096
.LBB0_526:
	s_or_b64 exec, exec, s[10:11]
	v_max_f32_e32 v50, v49, v49
	s_waitcnt lgkmcnt(0)
	v_max_f32_e32 v51, v48, v48
	v_max_f32_e32 v50, v51, v50
	v_max_f32_e32 v51, v41, v41
	v_max_f32_e32 v52, v40, v40
	v_max_f32_e32 v51, v52, v51
	v_max3_f32 v50, v46, v47, v50
	v_max3_f32 v51, v38, v39, v51
	v_max3_f32 v50, v50, s18, v51
	v_max_f32_e32 v51, v45, v45
	v_max_f32_e32 v52, v44, v44
	v_max_f32_e32 v51, v52, v51
	v_max_f32_e32 v52, v37, v37
	v_max_f32_e32 v53, v36, v36
	v_max_f32_e32 v52, v53, v52
	v_max3_f32 v51, v42, v43, v51
	v_max3_f32 v52, v34, v35, v52
	v_max3_f32 v50, v50, v51, v52
	v_mov_b32_e32 v51, v50
	s_nop 1
	v_permlane16_swap_b32 v50, v51
	s_waitcnt lgkmcnt(0)
	v_max_f32_e32 v51, v51, v51
	v_max_f32_e32 v50, v50, v51
	v_mov_b32_e32 v51, v50
	s_nop 1
	v_permlane32_swap_b32 v50, v51
	s_waitcnt lgkmcnt(0)
	v_max_f32_e32 v51, v51, v51
	v_max_f32_e32 v58, v50, v51
	v_sub_f32_e32 v46, v46, v58
	v_exp_f32_e32 v50, v46
	v_sub_f32_e32 v46, v47, v58
	v_exp_f32_e32 v51, v46
	v_sub_f32_e32 v46, v48, v58
	v_exp_f32_e32 v54, v46
	v_sub_f32_e32 v46, v49, v58
	v_exp_f32_e32 v55, v46
	v_sub_f32_e32 v38, v38, v58
	v_exp_f32_e32 v48, v38
	v_sub_f32_e32 v38, v39, v58
	v_exp_f32_e32 v49, v38
	v_sub_f32_e32 v38, v40, v58
	v_exp_f32_e32 v56, v38
	v_sub_f32_e32 v38, v41, v58
	v_sub_f32_e32 v41, v42, v58
	v_add_f32_e32 v46, v50, v51
	v_add_f32_e32 v47, v54, v55
	v_exp_f32_e32 v42, v41
	v_sub_f32_e32 v41, v43, v58
	v_sub_f32_e32 v34, v34, v58
	v_exp_f32_e32 v57, v38
	v_add_f32_e32 v38, v46, v47
	v_exp_f32_e32 v43, v41
	v_sub_f32_e32 v41, v44, v58
	v_exp_f32_e32 v46, v34
	v_sub_f32_e32 v34, v35, v58
	v_exp_f32_e32 v44, v41
	v_sub_f32_e32 v41, v45, v58
	v_exp_f32_e32 v47, v34
	v_sub_f32_e32 v34, v36, v58
	v_exp_f32_e32 v45, v41
	v_exp_f32_e32 v52, v34
	v_sub_f32_e32 v34, v37, v58
	v_exp_f32_e32 v53, v34
	v_add_f32_e32 v39, v48, v49
	v_add_f32_e32 v40, v56, v57
	v_add_f32_e32 v38, 0, v38
	v_add_f32_e32 v39, v39, v40
	v_add_f32_e32 v38, v39, v38
	v_add_f32_e32 v39, v42, v43
	v_add_f32_e32 v40, v44, v45
	v_add_f32_e32 v34, v39, v40
	v_add_f32_e32 v35, v46, v47
	v_add_f32_e32 v36, v52, v53
	v_add_f32_e32 v34, v34, v38
	v_add_f32_e32 v35, v35, v36
	v_add_f32_e32 v34, v35, v34
	v_mov_b32_e32 v35, v34
	s_nop 1
	v_permlane16_swap_b32 v34, v35
	s_waitcnt lgkmcnt(0)
	v_add_f32_e32 v34, v34, v35
	v_mov_b32_e32 v35, v34
	s_nop 1
	v_permlane32_swap_b32 v34, v35
	s_and_saveexec_b64 s[10:11], s[0:1]
	s_cbranch_execz .LBB0_528
	s_waitcnt lgkmcnt(0)
	v_add_f32_e32 v59, v34, v35
	v_add_u32_e32 v34, 0, v157
	ds_write_b64 v34, v[58:59] offset:4608
;     __device__ __forceinline__ void operator()(Acc& acc, const Unit& u, int wr, int wc, int fr, int fq, LAS unsigned char* lds, const LAS float* rst) const {
;     ...
;                 float mx = -INFINITY;
; #pragma unroll
;                 for (int bj = 0; bj < 2; ++bj)
; #pragma unroll
;                     for (int n = 0; n < 2; ++n) { const f32x4 v = acc[ai][bj][m][n]; mx = fmaxf(mx, fmaxf(fmaxf(v[0], v[1]), fmaxf(v[2], v[3]))); }
;                 mx = fmaxf(mx, __shfl_xor(mx, 16)); mx = fmaxf(mx, __shfl_xor(mx, 32));
;                 float s = 0.f;
; #pragma unroll
;                 for (int bj = 0; bj < 2; ++bj)
; #pragma unroll
;                     for (int n = 0; n < 2; ++n) { f32x4 v = acc[ai][bj][m][n];
; #pragma unroll
;                         for (int j = 0; j < 4; ++j) v[j] = __builtin_amdgcn_exp2f(v[j] - mx);
;                         acc[ai][bj][m][n] = v; s += (v[0] + v[1]) + (v[2] + v[3]); }
;                 s += __shfl_xor(s, 16); s += __shfl_xor(s, 32);
;                 if (fq == 0) Xw[(ai * 128 + m * 16) * 4] = (f32x2){mx, s};
.LBB0_528:
	s_or_b64 exec, exec, s[10:11]
	v_max_f32_e32 v34, v33, v33
	s_waitcnt lgkmcnt(0)
	v_max_f32_e32 v35, v32, v32
	v_max_f32_e32 v34, v35, v34
	v_max_f32_e32 v35, v25, v25
	v_max_f32_e32 v36, v24, v24
	v_max_f32_e32 v35, v36, v35
	v_max3_f32 v34, v30, v31, v34
	v_max3_f32 v35, v22, v23, v35
	v_max3_f32 v34, v34, s18, v35
	v_max_f32_e32 v35, v29, v29
	v_max_f32_e32 v36, v28, v28
	v_max_f32_e32 v35, v36, v35
	v_max_f32_e32 v36, v21, v21
	v_max_f32_e32 v37, v20, v20
	v_max_f32_e32 v36, v37, v36
	v_max3_f32 v35, v26, v27, v35
	v_max3_f32 v36, v18, v19, v36
	v_max3_f32 v34, v34, v35, v36
	v_mov_b32_e32 v35, v34
	s_nop 1
	v_permlane16_swap_b32 v34, v35
	s_waitcnt lgkmcnt(0)
	v_max_f32_e32 v35, v35, v35
	v_max_f32_e32 v34, v34, v35
	v_mov_b32_e32 v35, v34
	s_nop 1
	v_permlane32_swap_b32 v34, v35
	s_waitcnt lgkmcnt(0)
	v_max_f32_e32 v35, v35, v35
	v_max_f32_e32 v58, v34, v35
	v_sub_f32_e32 v30, v30, v58
	v_exp_f32_e32 v34, v30
	v_sub_f32_e32 v30, v31, v58
	v_exp_f32_e32 v35, v30
	v_sub_f32_e32 v30, v32, v58
	v_exp_f32_e32 v38, v30
	v_sub_f32_e32 v30, v33, v58
	v_exp_f32_e32 v39, v30
	v_sub_f32_e32 v22, v22, v58
	v_exp_f32_e32 v32, v22
	v_sub_f32_e32 v22, v23, v58
	v_exp_f32_e32 v33, v22
	v_sub_f32_e32 v22, v24, v58
	v_exp_f32_e32 v40, v22
	v_sub_f32_e32 v22, v25, v58
	v_sub_f32_e32 v25, v26, v58
	v_add_f32_e32 v30, v34, v35
	v_add_f32_e32 v31, v38, v39
	v_exp_f32_e32 v26, v25
	v_sub_f32_e32 v25, v27, v58
	v_sub_f32_e32 v18, v18, v58
	v_exp_f32_e32 v41, v22
	v_add_f32_e32 v22, v30, v31
	v_exp_f32_e32 v27, v25
	v_sub_f32_e32 v25, v28, v58
	v_exp_f32_e32 v30, v18
	v_sub_f32_e32 v18, v19, v58
	v_exp_f32_e32 v28, v25
	v_sub_f32_e32 v25, v29, v58
	v_exp_f32_e32 v31, v18
	v_sub_f32_e32 v18, v20, v58
	v_exp_f32_e32 v29, v25
	v_exp_f32_e32 v36, v18
	v_sub_f32_e32 v18, v21, v58
	v_exp_f32_e32 v37, v18
	v_add_f32_e32 v23, v32, v33
	v_add_f32_e32 v24, v40, v41
	v_add_f32_e32 v22, 0, v22
	v_add_f32_e32 v23, v23, v24
	v_add_f32_e32 v22, v23, v22
	v_add_f32_e32 v23, v26, v27
	v_add_f32_e32 v24, v28, v29
	v_add_f32_e32 v18, v23, v24
	v_add_f32_e32 v19, v30, v31
	v_add_f32_e32 v20, v36, v37
	v_add_f32_e32 v18, v18, v22
	v_add_f32_e32 v19, v19, v20
	v_add_f32_e32 v18, v19, v18
	v_mov_b32_e32 v19, v18
	s_nop 1
	v_permlane16_swap_b32 v18, v19
	s_waitcnt lgkmcnt(0)
	v_add_f32_e32 v18, v18, v19
	v_mov_b32_e32 v19, v18
	s_nop 1
	v_permlane32_swap_b32 v18, v19
	s_and_saveexec_b64 s[10:11], s[0:1]
	s_cbranch_execz .LBB0_530
	s_waitcnt lgkmcnt(0)
	v_add_f32_e32 v59, v18, v19
	v_add_u32_e32 v18, 0, v157
	ds_write_b64 v18, v[58:59] offset:5120
.LBB0_530:
	s_or_b64 exec, exec, s[10:11]
	v_max_f32_e32 v18, v17, v17
	s_waitcnt lgkmcnt(0)
	v_max_f32_e32 v19, v16, v16
	v_max_f32_e32 v18, v19, v18
	v_max_f32_e32 v19, v9, v9
	v_max_f32_e32 v20, v8, v8
	v_max_f32_e32 v19, v20, v19
	v_max3_f32 v18, v14, v15, v18
	v_max3_f32 v19, v6, v7, v19
	v_max3_f32 v18, v18, s18, v19
	v_max_f32_e32 v19, v13, v13
	v_max_f32_e32 v20, v12, v12
	v_max_f32_e32 v19, v20, v19
	v_max_f32_e32 v20, v5, v5
	v_max_f32_e32 v21, v4, v4
	v_max_f32_e32 v20, v21, v20
	v_max3_f32 v19, v10, v11, v19
	v_max3_f32 v20, v2, v3, v20
	v_max3_f32 v18, v18, v19, v20
	v_mov_b32_e32 v19, v18
	s_nop 1
	v_permlane16_swap_b32 v18, v19
	s_waitcnt lgkmcnt(0)
	v_max_f32_e32 v19, v19, v19
	v_max_f32_e32 v18, v18, v19
	v_mov_b32_e32 v19, v18
	s_nop 1
	v_permlane32_swap_b32 v18, v19
	s_waitcnt lgkmcnt(0)
	v_max_f32_e32 v19, v19, v19
	v_max_f32_e32 v58, v18, v19
	v_sub_f32_e32 v14, v14, v58
	v_exp_f32_e32 v18, v14
	v_sub_f32_e32 v14, v15, v58
	v_exp_f32_e32 v19, v14
	v_sub_f32_e32 v14, v16, v58
	v_exp_f32_e32 v22, v14
	v_sub_f32_e32 v14, v17, v58
	v_exp_f32_e32 v23, v14
	v_sub_f32_e32 v6, v6, v58
	v_exp_f32_e32 v16, v6
	v_sub_f32_e32 v6, v7, v58
	v_exp_f32_e32 v17, v6
	v_sub_f32_e32 v6, v8, v58
	v_exp_f32_e32 v24, v6
	v_sub_f32_e32 v6, v9, v58
	v_sub_f32_e32 v9, v10, v58
	v_add_f32_e32 v14, v18, v19
	v_add_f32_e32 v15, v22, v23
	v_exp_f32_e32 v10, v9
	v_sub_f32_e32 v9, v11, v58
	v_sub_f32_e32 v2, v2, v58
	v_exp_f32_e32 v25, v6
	v_add_f32_e32 v6, v14, v15
	v_exp_f32_e32 v11, v9
	v_sub_f32_e32 v9, v12, v58
	v_exp_f32_e32 v14, v2
	v_sub_f32_e32 v2, v3, v58
	v_exp_f32_e32 v12, v9
	v_sub_f32_e32 v9, v13, v58
	v_exp_f32_e32 v15, v2
	v_sub_f32_e32 v2, v4, v58
	v_exp_f32_e32 v13, v9
	v_exp_f32_e32 v20, v2
	v_sub_f32_e32 v2, v5, v58
	v_exp_f32_e32 v21, v2
	v_add_f32_e32 v7, v16, v17
	v_add_f32_e32 v8, v24, v25
	v_add_f32_e32 v6, 0, v6
	v_add_f32_e32 v7, v7, v8
	v_add_f32_e32 v6, v7, v6
	v_add_f32_e32 v7, v10, v11
	v_add_f32_e32 v8, v12, v13
	v_add_f32_e32 v2, v7, v8
	v_add_f32_e32 v3, v14, v15
	v_add_f32_e32 v4, v20, v21
	v_add_f32_e32 v2, v2, v6
	v_add_f32_e32 v3, v3, v4
	v_add_f32_e32 v2, v3, v2
	v_mov_b32_e32 v3, v2
	s_nop 1
	v_permlane16_swap_b32 v2, v3
	s_waitcnt lgkmcnt(0)
	v_add_f32_e32 v2, v2, v3
	v_mov_b32_e32 v3, v2
	s_nop 1
	v_permlane32_swap_b32 v2, v3
	s_and_saveexec_b64 s[10:11], s[0:1]
	s_cbranch_execz .LBB0_532
	s_waitcnt lgkmcnt(0)
	v_add_f32_e32 v59, v2, v3
	v_add_u32_e32 v2, 0, v157
	ds_write_b64 v2, v[58:59] offset:5632

; __device__ __forceinline__ unsigned cvt_pk_bf16(float lo, float hi) { unsigned r; asm volatile("v_cvt_pk_bf16_f32 %0, %1, %2" : "=v"(r) : "v"(lo), "v"(hi)); return r; }
; __device__ __forceinline__ float bf_lo(unsigned w) { return __uint_as_float(w << 16); }
; __device__ __forceinline__ float bf_hi(unsigned w) { return __uint_as_float(w & 0xffff0000u); }
;     __device__ __forceinline__ void operator()(Acc& acc, const Unit& u, int wr, int wc, int fr, int fq, LAS unsigned char*, const LAS float* rst) const {
;     ...
;         for (int ai = 0; ai < 2; ++ai) {
;             u32x4 xo[4][2];
; #pragma unroll
;             for (int m = 0; m < 4; ++m) { const size_t off = (size_t)(row0 + ai * 128 + m * 16) * D + col0;
; #pragma unroll
;                 for (int bj = 0; bj < 2; ++bj) xo[m][bj] = *(const u32x4*)(XB + off + bj * 128); }
;             asm volatile("" ::: "memory");
; #pragma unroll
;             for (int m = 0; m < 4; ++m) {
;                 const int row = row0 + ai * 128 + m * 16; const size_t off = (size_t)row * D + col0; float s = 0.f;
; #pragma unroll
;                 for (int bj = 0; bj < 2; ++bj) { const f32x4 a0 = acc[ai][bj][m][0], a1 = acc[ai][bj][m][1]; const u32x4 o = xo[m][bj];
;                     const float n0 = bf_lo(o.x) + a0[0] * scale, n1 = bf_hi(o.x) + a0[1] * scale, n2 = bf_lo(o.y) + a0[2] * scale, n3 = bf_hi(o.y) + a0[3] * scale;
;                     const float n4 = bf_lo(o.z) + a1[0] * scale, n5 = bf_hi(o.z) + a1[1] * scale, n6 = bf_lo(o.w) + a1[2] * scale, n7 = bf_hi(o.w) + a1[3] * scale;
;                     u32x4 w; w.x = cvt_pk_bf16(n0, n1); w.y = cvt_pk_bf16(n2, n3); w.z = cvt_pk_bf16(n4, n5); w.w = cvt_pk_bf16(n6, n7); *(u32x4*)(XB + off + bj * 128) = w;
;                     s += ((n0 * n0 + n1 * n1) + (n2 * n2 + n3 * n3)) + ((n4 * n4 + n5 * n5) + (n6 * n6 + n7 * n7)); }
;                 s += __shfl_xor(s, 16); s += __shfl_xor(s, 32);
;                 if (fq == 0) ssq[(size_t)row * 16 + u.pn * 4 + wc] = s;
;             }
.LBB0_730:
	v_lshl_or_b32 v166, s10, 8, v193
	v_lshl_add_u32 v170, s18, 8, v191
	v_ashrrev_i32_e32 v167, 31, v166
	v_lshlrev_b64 v[204:205], 1, v[166:167]
	v_ashrrev_i32_e32 v171, 31, v170
	v_lshl_add_u64 v[168:169], s[14:15], 0, v[204:205]
	v_lshlrev_b64 v[206:207], 11, v[170:171]
	v_lshl_add_u64 v[114:115], v[168:169], 0, v[206:207]
	global_load_dwordx4 v[196:199], v[114:115], off
	global_load_dwordx4 v[200:203], v[114:115], off offset:256
	v_or_b32_e32 v180, 16, v170
	v_ashrrev_i32_e32 v181, 31, v180
	v_or_b32_e32 v176, 32, v170
	v_lshlrev_b64 v[182:183], 11, v[180:181]
	v_ashrrev_i32_e32 v177, 31, v176
	v_or_b32_e32 v172, 48, v170
	v_lshl_add_u64 v[114:115], v[168:169], 0, v[182:183]
	v_lshlrev_b64 v[178:179], 11, v[176:177]
	v_ashrrev_i32_e32 v173, 31, v172
	global_load_dwordx4 v[134:137], v[114:115], off
	global_load_dwordx4 v[130:133], v[114:115], off offset:256
	v_lshl_add_u64 v[114:115], v[168:169], 0, v[178:179]
	v_lshlrev_b64 v[174:175], 11, v[172:173]
	global_load_dwordx4 v[126:129], v[114:115], off
	global_load_dwordx4 v[122:125], v[114:115], off offset:256
	v_lshl_add_u64 v[114:115], v[168:169], 0, v[174:175]
	global_load_dwordx4 v[118:121], v[114:115], off
	s_nop 0
	global_load_dwordx4 v[114:117], v[114:115], off offset:256
	s_lshl_b32 s42, s10, 2
	s_ashr_i32 s43, s42, 31
	v_add_u32_e32 v240, 0x80, v170
	v_ashrrev_i32_e32 v241, 31, v240
	v_lshlrev_b64 v[240:241], 11, v[240:241]
	v_lshl_add_u64 v[242:243], v[168:169], 0, v[240:241]
	global_load_dwordx4 v[208:211], v[242:243], off
	global_load_dwordx4 v[212:215], v[242:243], off offset:256
	v_add_u32_e32 v240, 0x90, v170
	v_ashrrev_i32_e32 v241, 31, v240
	v_lshlrev_b64 v[240:241], 11, v[240:241]
	v_lshl_add_u64 v[242:243], v[168:169], 0, v[240:241]
	global_load_dwordx4 v[216:219], v[242:243], off
	global_load_dwordx4 v[220:223], v[242:243], off offset:256
	v_add_u32_e32 v240, 0xa0, v170
	v_ashrrev_i32_e32 v241, 31, v240
	v_lshlrev_b64 v[240:241], 11, v[240:241]
	v_lshl_add_u64 v[242:243], v[168:169], 0, v[240:241]
	global_load_dwordx4 v[224:227], v[242:243], off
	global_load_dwordx4 v[228:231], v[242:243], off offset:256
	v_add_u32_e32 v240, 0xb0, v170
	v_ashrrev_i32_e32 v241, 31, v240
	v_lshlrev_b64 v[240:241], 11, v[240:241]
	v_lshl_add_u64 v[242:243], v[168:169], 0, v[240:241]
	global_load_dwordx4 v[232:235], v[242:243], off
	global_load_dwordx4 v[236:239], v[242:243], off offset:256
	s_waitcnt vmcnt(0) lgkmcnt(0)
	v_lshlrev_b32_e32 v190, 16, v196
	v_and_b32_e32 v195, 0xffff0000, v196
	v_lshlrev_b32_e32 v196, 16, v197
	v_fmac_f32_e32 v196, s2, v152
	v_and_b32_e32 v152, 0xffff0000, v197
	v_fmac_f32_e32 v190, s2, v150
	v_fmac_f32_e32 v195, s2, v151
	v_fmac_f32_e32 v152, s2, v153
	v_lshlrev_b32_e32 v153, 16, v198
	v_and_b32_e32 v197, 0xffff0000, v198
	v_lshl_add_u64 v[150:151], s[14:15], 0, v[206:207]
	v_fmac_f32_e32 v153, s2, v146
	v_fmac_f32_e32 v197, s2, v147
	v_lshlrev_b32_e32 v198, 16, v199
	v_and_b32_e32 v199, 0xffff0000, v199
	v_cvt_pk_bf16_f32 v146, v190, v195
	v_cvt_pk_bf16_f32 v147, v196, v152
	v_lshl_add_u64 v[150:151], v[150:151], 0, v[204:205]
	v_fmac_f32_e32 v198, s2, v148
	v_fmac_f32_e32 v199, s2, v149
	v_cvt_pk_bf16_f32 v148, v153, v197
	v_cvt_pk_bf16_f32 v149, v198, v199
	global_store_dwordx4 v[150:151], v[146:149], off
	s_nop 1
	v_mul_f32_e32 v146, v195, v195
	v_mul_f32_e32 v147, v152, v152
	v_fmac_f32_e32 v146, v190, v190
	v_fmac_f32_e32 v147, v196, v196
	v_add_f32_e32 v146, v146, v147
	v_mul_f32_e32 v147, v197, v197
	v_mul_f32_e32 v148, v199, v199
	v_fmac_f32_e32 v147, v153, v153
	v_fmac_f32_e32 v148, v198, v198
	v_add_f32_e32 v147, v147, v148
	v_add_f32_e32 v146, v146, v147
	v_lshlrev_b32_e32 v147, 16, v200
	v_fmac_f32_e32 v147, s2, v142
	v_and_b32_e32 v142, 0xffff0000, v200
	v_fmac_f32_e32 v142, s2, v143
	v_lshlrev_b32_e32 v143, 16, v201
	v_fmac_f32_e32 v143, s2, v144
	v_and_b32_e32 v144, 0xffff0000, v201
	v_fmac_f32_e32 v144, s2, v145
	v_lshlrev_b32_e32 v145, 16, v202
	v_and_b32_e32 v148, 0xffff0000, v202
	v_fmac_f32_e32 v145, s2, v138
	v_fmac_f32_e32 v148, s2, v139
	v_lshlrev_b32_e32 v149, 16, v203
	v_and_b32_e32 v152, 0xffff0000, v203
	v_cvt_pk_bf16_f32 v138, v147, v142
	v_cvt_pk_bf16_f32 v139, v143, v144
	v_fmac_f32_e32 v149, s2, v140
	v_fmac_f32_e32 v152, s2, v141
	v_cvt_pk_bf16_f32 v140, v145, v148
	v_cvt_pk_bf16_f32 v141, v149, v152
	global_store_dwordx4 v[150:151], v[138:141], off offset:256
	s_nop 1
	v_mul_f32_e32 v138, v142, v142
	v_mul_f32_e32 v139, v144, v144
	v_fmac_f32_e32 v138, v147, v147
	v_fmac_f32_e32 v139, v143, v143
	v_add_f32_e32 v138, v138, v139
	v_mul_f32_e32 v139, v148, v148
	v_mul_f32_e32 v140, v152, v152
	v_fmac_f32_e32 v139, v145, v145
	v_fmac_f32_e32 v140, v149, v149
	v_add_f32_e32 v139, v139, v140
	v_add_f32_e32 v138, v138, v139
	v_and_b32_e32 v140, 64, v185
	v_add_f32_e32 v139, v146, v138
	v_xor_b32_e32 v138, 16, v185
	v_add_u32_e32 v141, 64, v140
	v_cmp_lt_i32_e32 vcc, v138, v141
	s_nop 1
	v_cndmask_b32_e32 v138, v185, v138, vcc
	v_lshlrev_b32_e32 v138, 2, v138
	v_mov_b32_e32 v140, v139
	s_nop 1
	v_permlane16_swap_b32 v139, v140
	s_waitcnt lgkmcnt(0)
	v_add_f32_e32 v140, v139, v140
	v_xor_b32_e32 v139, 32, v185
	v_cmp_lt_i32_e32 vcc, v139, v141
	s_nop 1
	v_cndmask_b32_e32 v139, v185, v139, vcc
	v_lshlrev_b32_e32 v139, 2, v139
	v_mov_b32_e32 v141, v140
	s_nop 1
	v_permlane32_swap_b32 v140, v141
	s_and_saveexec_b64 s[10:11], s[0:1]
	s_cbranch_execz .LBB0_732
	v_lshlrev_b64 v[142:143], 6, v[170:171]
	v_lshl_add_u64 v[142:143], s[12:13], 0, v[142:143]
	v_lshl_add_u64 v[142:143], s[42:43], 2, v[142:143]
	s_lshl_b32 s46, s95, 2
	v_lshl_add_u64 v[142:143], v[142:143], 0, s[46:47]
	s_waitcnt lgkmcnt(0)
	v_add_f32_e32 v140, v140, v141
	global_store_dword v[142:143], v140, off
; __device__ __forceinline__ unsigned cvt_pk_bf16(float lo, float hi) { unsigned r; asm volatile("v_cvt_pk_bf16_f32 %0, %1, %2" : "=v"(r) : "v"(lo), "v"(hi)); return r; }
; __device__ __forceinline__ float bf_lo(unsigned w) { return __uint_as_float(w << 16); }
; __device__ __forceinline__ float bf_hi(unsigned w) { return __uint_as_float(w & 0xffff0000u); }
;     __device__ __forceinline__ void operator()(Acc& acc, const Unit& u, int wr, int wc, int fr, int fq, LAS unsigned char*, const LAS float* rst) const {
;     ...
;             for (int m = 0; m < 4; ++m) {
;                 const int row = row0 + ai * 128 + m * 16; const size_t off = (size_t)row * D + col0; float s = 0.f;
; #pragma unroll
;                 for (int bj = 0; bj < 2; ++bj) { const f32x4 a0 = acc[ai][bj][m][0], a1 = acc[ai][bj][m][1]; const u32x4 o = xo[m][bj];
;                     const float n0 = bf_lo(o.x) + a0[0] * scale, n1 = bf_hi(o.x) + a0[1] * scale, n2 = bf_lo(o.y) + a0[2] * scale, n3 = bf_hi(o.y) + a0[3] * scale;
;                     const float n4 = bf_lo(o.z) + a1[0] * scale, n5 = bf_hi(o.z) + a1[1] * scale, n6 = bf_lo(o.w) + a1[2] * scale, n7 = bf_hi(o.w) + a1[3] * scale;
;                     u32x4 w; w.x = cvt_pk_bf16(n0, n1); w.y = cvt_pk_bf16(n2, n3); w.z = cvt_pk_bf16(n4, n5); w.w = cvt_pk_bf16(n6, n7); *(u32x4*)(XB + off + bj * 128) = w;
;                     s += ((n0 * n0 + n1 * n1) + (n2 * n2 + n3 * n3)) + ((n4 * n4 + n5 * n5) + (n6 * n6 + n7 * n7)); }
;                 s += __shfl_xor(s, 16); s += __shfl_xor(s, 32);
;                 if (fq == 0) ssq[(size_t)row * 16 + u.pn * 4 + wc] = s;
;             }
.LBB0_732:
	s_or_b64 exec, exec, s[10:11]
	v_lshlrev_b32_e32 v140, 16, v134
	v_fmac_f32_e32 v140, s2, v110
	v_and_b32_e32 v110, 0xffff0000, v134
	v_fmac_f32_e32 v110, s2, v111
	v_lshlrev_b32_e32 v111, 16, v135
	v_fmac_f32_e32 v111, s2, v112
	v_and_b32_e32 v112, 0xffff0000, v135
	v_fmac_f32_e32 v112, s2, v113
	v_lshlrev_b32_e32 v113, 16, v136
	v_and_b32_e32 v134, 0xffff0000, v136
	v_fmac_f32_e32 v113, s2, v106
	v_fmac_f32_e32 v134, s2, v107
	v_and_b32_e32 v136, 0xffff0000, v137
	v_cvt_pk_bf16_f32 v106, v140, v110
	v_cvt_pk_bf16_f32 v107, v111, v112
	v_mul_f32_e32 v110, v110, v110
	v_mul_f32_e32 v112, v112, v112
	v_lshlrev_b32_e32 v135, 16, v137
	v_fmac_f32_e32 v136, s2, v109
	v_fmac_f32_e32 v110, v140, v140
	v_fmac_f32_e32 v112, v111, v111
	v_fmac_f32_e32 v135, s2, v108
	v_add_f32_e32 v110, v110, v112
	v_mul_f32_e32 v111, v134, v134
	v_mul_f32_e32 v112, v136, v136
	v_fmac_f32_e32 v111, v113, v113
	v_fmac_f32_e32 v112, v135, v135
	v_add_f32_e32 v111, v111, v112
	v_add_f32_e32 v110, v110, v111
	v_lshlrev_b32_e32 v111, 16, v130
	v_fmac_f32_e32 v111, s2, v102
	v_and_b32_e32 v102, 0xffff0000, v130
	v_and_b32_e32 v112, 0xffff0000, v131
	v_cvt_pk_bf16_f32 v108, v113, v134
	v_fmac_f32_e32 v102, s2, v103
	v_lshlrev_b32_e32 v103, 16, v131
	v_fmac_f32_e32 v112, s2, v105
	v_lshlrev_b32_e32 v113, 16, v132
	v_and_b32_e32 v130, 0xffff0000, v132
	v_fmac_f32_e32 v103, s2, v104
	v_fmac_f32_e32 v113, s2, v98
	v_fmac_f32_e32 v130, s2, v99
	v_and_b32_e32 v132, 0xffff0000, v133
	v_mul_f32_e32 v98, v102, v102
	v_mul_f32_e32 v99, v112, v112
	v_lshlrev_b32_e32 v131, 16, v133
	v_fmac_f32_e32 v132, s2, v101
	v_fmac_f32_e32 v98, v111, v111
	v_fmac_f32_e32 v99, v103, v103
	v_fmac_f32_e32 v131, s2, v100
	v_add_f32_e32 v98, v98, v99
	v_mul_f32_e32 v99, v130, v130
	v_mul_f32_e32 v100, v132, v132
	v_fmac_f32_e32 v99, v113, v113
	v_fmac_f32_e32 v100, v131, v131
	v_add_f32_e32 v99, v99, v100
	v_add_f32_e32 v98, v98, v99
	v_add_f32_e32 v101, v110, v98
	v_mov_b32_e32 v110, v101
	s_nop 1
	v_permlane16_swap_b32 v101, v110
	v_lshl_add_u64 v[98:99], s[14:15], 0, v[182:183]
	v_lshl_add_u64 v[104:105], v[166:167], 1, v[98:99]
	v_cvt_pk_bf16_f32 v109, v135, v136
	global_store_dwordx4 v[104:105], v[106:109], off
	s_waitcnt lgkmcnt(0)
	v_add_f32_e32 v98, v101, v110
	v_mov_b32_e32 v99, v98
	s_nop 1
	v_permlane32_swap_b32 v98, v99
	v_cvt_pk_bf16_f32 v100, v111, v102
	v_cvt_pk_bf16_f32 v101, v103, v112
	v_cvt_pk_bf16_f32 v102, v113, v130
	v_cvt_pk_bf16_f32 v103, v131, v132
	global_store_dwordx4 v[104:105], v[100:103], off offset:256
	s_and_saveexec_b64 s[10:11], s[0:1]
	s_cbranch_execz .LBB0_734
	v_lshlrev_b64 v[100:101], 6, v[180:181]
	v_lshl_add_u64 v[100:101], s[12:13], 0, v[100:101]
	v_lshl_add_u64 v[100:101], s[42:43], 2, v[100:101]
	s_lshl_b32 s46, s95, 2
	v_lshl_add_u64 v[100:101], v[100:101], 0, s[46:47]
	s_waitcnt lgkmcnt(0)
	v_add_f32_e32 v98, v98, v99
	global_store_dword v[100:101], v98, off
.LBB0_734:
	s_or_b64 exec, exec, s[10:11]
	v_lshlrev_b32_e32 v98, 16, v126
	v_fmac_f32_e32 v98, s2, v94
	v_and_b32_e32 v94, 0xffff0000, v126
	v_fmac_f32_e32 v94, s2, v95
	v_lshlrev_b32_e32 v95, 16, v127
	v_fmac_f32_e32 v95, s2, v96
	v_and_b32_e32 v96, 0xffff0000, v127
	v_fmac_f32_e32 v96, s2, v97
	v_lshlrev_b32_e32 v97, 16, v128
	s_waitcnt lgkmcnt(0)
	v_and_b32_e32 v99, 0xffff0000, v128
	v_fmac_f32_e32 v97, s2, v90
	v_fmac_f32_e32 v99, s2, v91
	v_and_b32_e32 v101, 0xffff0000, v129
	v_cvt_pk_bf16_f32 v90, v98, v94
	v_cvt_pk_bf16_f32 v91, v95, v96
	v_mul_f32_e32 v94, v94, v94
	v_mul_f32_e32 v96, v96, v96
	v_lshlrev_b32_e32 v100, 16, v129
	v_fmac_f32_e32 v101, s2, v93
	v_fmac_f32_e32 v94, v98, v98
	v_fmac_f32_e32 v96, v95, v95
	v_fmac_f32_e32 v100, s2, v92
	v_add_f32_e32 v94, v94, v96
	v_mul_f32_e32 v95, v99, v99
	v_mul_f32_e32 v96, v101, v101
	v_fmac_f32_e32 v95, v97, v97
	v_fmac_f32_e32 v96, v100, v100
	v_add_f32_e32 v95, v95, v96
	v_add_f32_e32 v94, v94, v95
	v_lshlrev_b32_e32 v95, 16, v122
	v_fmac_f32_e32 v95, s2, v86
	v_and_b32_e32 v86, 0xffff0000, v122
	v_and_b32_e32 v96, 0xffff0000, v123
	v_cvt_pk_bf16_f32 v92, v97, v99
	v_fmac_f32_e32 v86, s2, v87
	v_lshlrev_b32_e32 v87, 16, v123
	v_fmac_f32_e32 v96, s2, v89
	v_lshlrev_b32_e32 v97, 16, v124
	v_and_b32_e32 v98, 0xffff0000, v124
	v_cvt_pk_bf16_f32 v93, v100, v101
	v_fmac_f32_e32 v87, s2, v88
	v_fmac_f32_e32 v97, s2, v82
	v_fmac_f32_e32 v98, s2, v83
	v_and_b32_e32 v100, 0xffff0000, v125
	v_mul_f32_e32 v82, v86, v86
	v_mul_f32_e32 v83, v96, v96
	v_lshlrev_b32_e32 v99, 16, v125
	v_fmac_f32_e32 v100, s2, v85
	v_fmac_f32_e32 v82, v95, v95
	v_fmac_f32_e32 v83, v87, v87
	v_fmac_f32_e32 v99, s2, v84
	v_add_f32_e32 v82, v82, v83
	v_mul_f32_e32 v83, v98, v98
	v_mul_f32_e32 v84, v100, v100
	v_fmac_f32_e32 v83, v97, v97
	v_fmac_f32_e32 v84, v99, v99
	v_add_f32_e32 v83, v83, v84
	v_add_f32_e32 v82, v82, v83
	v_add_f32_e32 v85, v94, v82
	v_mov_b32_e32 v94, v85
	s_nop 1
	v_permlane16_swap_b32 v85, v94
	v_lshl_add_u64 v[82:83], s[14:15], 0, v[178:179]
	v_lshl_add_u64 v[88:89], v[166:167], 1, v[82:83]
	global_store_dwordx4 v[88:89], v[90:93], off
	v_cvt_pk_bf16_f32 v84, v95, v86
	s_waitcnt lgkmcnt(0)
	v_add_f32_e32 v82, v85, v94
	v_mov_b32_e32 v83, v82
	s_nop 1
	v_permlane32_swap_b32 v82, v83
	v_cvt_pk_bf16_f32 v85, v87, v96
	v_cvt_pk_bf16_f32 v86, v97, v98
	v_cvt_pk_bf16_f32 v87, v99, v100
	global_store_dwordx4 v[88:89], v[84:87], off offset:256
	s_and_saveexec_b64 s[10:11], s[0:1]
	s_cbranch_execz .LBB0_736
	v_lshlrev_b64 v[84:85], 6, v[176:177]
	v_lshl_add_u64 v[84:85], s[12:13], 0, v[84:85]
	v_lshl_add_u64 v[84:85], s[42:43], 2, v[84:85]
	s_lshl_b32 s46, s95, 2
	v_lshl_add_u64 v[84:85], v[84:85], 0, s[46:47]
	s_waitcnt lgkmcnt(0)
	v_add_f32_e32 v82, v82, v83
	global_store_dword v[84:85], v82, off
; __device__ __forceinline__ unsigned cvt_pk_bf16(float lo, float hi) { unsigned r; asm volatile("v_cvt_pk_bf16_f32 %0, %1, %2" : "=v"(r) : "v"(lo), "v"(hi)); return r; }
; __device__ __forceinline__ float bf_lo(unsigned w) { return __uint_as_float(w << 16); }
; __device__ __forceinline__ float bf_hi(unsigned w) { return __uint_as_float(w & 0xffff0000u); }
;     __device__ __forceinline__ void operator()(Acc& acc, const Unit& u, int wr, int wc, int fr, int fq, LAS unsigned char*, const LAS float* rst) const {
;     ...
;         for (int ai = 0; ai < 2; ++ai) {
;             u32x4 xo[4][2];
; #pragma unroll
;             for (int m = 0; m < 4; ++m) { const size_t off = (size_t)(row0 + ai * 128 + m * 16) * D + col0;
; #pragma unroll
;                 for (int bj = 0; bj < 2; ++bj) xo[m][bj] = *(const u32x4*)(XB + off + bj * 128); }
;             asm volatile("" ::: "memory");
; #pragma unroll
;             for (int m = 0; m < 4; ++m) {
;                 const int row = row0 + ai * 128 + m * 16; const size_t off = (size_t)row * D + col0; float s = 0.f;
; #pragma unroll
;                 for (int bj = 0; bj < 2; ++bj) { const f32x4 a0 = acc[ai][bj][m][0], a1 = acc[ai][bj][m][1]; const u32x4 o = xo[m][bj];
;                     const float n0 = bf_lo(o.x) + a0[0] * scale, n1 = bf_hi(o.x) + a0[1] * scale, n2 = bf_lo(o.y) + a0[2] * scale, n3 = bf_hi(o.y) + a0[3] * scale;
;                     const float n4 = bf_lo(o.z) + a1[0] * scale, n5 = bf_hi(o.z) + a1[1] * scale, n6 = bf_lo(o.w) + a1[2] * scale, n7 = bf_hi(o.w) + a1[3] * scale;
;                     u32x4 w; w.x = cvt_pk_bf16(n0, n1); w.y = cvt_pk_bf16(n2, n3); w.z = cvt_pk_bf16(n4, n5); w.w = cvt_pk_bf16(n6, n7); *(u32x4*)(XB + off + bj * 128) = w;
;                     s += ((n0 * n0 + n1 * n1) + (n2 * n2 + n3 * n3)) + ((n4 * n4 + n5 * n5) + (n6 * n6 + n7 * n7)); }
;                 s += __shfl_xor(s, 16); s += __shfl_xor(s, 32);
;                 if (fq == 0) ssq[(size_t)row * 16 + u.pn * 4 + wc] = s;
;             }
.LBB0_736:
	s_or_b64 exec, exec, s[10:11]
	v_lshlrev_b32_e32 v82, 16, v118
	v_fmac_f32_e32 v82, s2, v78
	v_and_b32_e32 v78, 0xffff0000, v118
	v_fmac_f32_e32 v78, s2, v79
	v_lshlrev_b32_e32 v79, 16, v119
	v_fmac_f32_e32 v79, s2, v80
	v_and_b32_e32 v80, 0xffff0000, v119
	v_fmac_f32_e32 v80, s2, v81
	v_lshlrev_b32_e32 v81, 16, v120
	s_waitcnt lgkmcnt(0)
	v_and_b32_e32 v83, 0xffff0000, v120
	v_fmac_f32_e32 v81, s2, v74
	v_fmac_f32_e32 v83, s2, v75
	v_and_b32_e32 v85, 0xffff0000, v121
	v_cvt_pk_bf16_f32 v74, v82, v78
	v_cvt_pk_bf16_f32 v75, v79, v80
	v_mul_f32_e32 v78, v78, v78
	v_mul_f32_e32 v80, v80, v80
	v_lshlrev_b32_e32 v84, 16, v121
	v_fmac_f32_e32 v85, s2, v77
	v_fmac_f32_e32 v78, v82, v82
	v_fmac_f32_e32 v80, v79, v79
	v_fmac_f32_e32 v84, s2, v76
	v_add_f32_e32 v78, v78, v80
	v_mul_f32_e32 v79, v83, v83
	v_mul_f32_e32 v80, v85, v85
	v_fmac_f32_e32 v79, v81, v81
	v_fmac_f32_e32 v80, v84, v84
	v_add_f32_e32 v79, v79, v80
	v_add_f32_e32 v78, v78, v79
	v_lshlrev_b32_e32 v79, 16, v114
	v_fmac_f32_e32 v79, s2, v70
	v_and_b32_e32 v70, 0xffff0000, v114
	v_and_b32_e32 v80, 0xffff0000, v115
	v_cvt_pk_bf16_f32 v76, v81, v83
	v_fmac_f32_e32 v70, s2, v71
	v_lshlrev_b32_e32 v71, 16, v115
	v_fmac_f32_e32 v80, s2, v73
	v_lshlrev_b32_e32 v81, 16, v116
	v_and_b32_e32 v82, 0xffff0000, v116
	v_cvt_pk_bf16_f32 v77, v84, v85
	v_fmac_f32_e32 v71, s2, v72
	v_fmac_f32_e32 v81, s2, v66
	v_fmac_f32_e32 v82, s2, v67
	v_and_b32_e32 v84, 0xffff0000, v117
	v_mul_f32_e32 v66, v70, v70
	v_mul_f32_e32 v67, v80, v80
	v_lshlrev_b32_e32 v83, 16, v117
	v_fmac_f32_e32 v84, s2, v69
	v_fmac_f32_e32 v66, v79, v79
	v_fmac_f32_e32 v67, v71, v71
	v_fmac_f32_e32 v83, s2, v68
	v_add_f32_e32 v66, v66, v67
	v_mul_f32_e32 v67, v82, v82
	v_mul_f32_e32 v68, v84, v84
	v_fmac_f32_e32 v67, v81, v81
	v_fmac_f32_e32 v68, v83, v83
	v_add_f32_e32 v67, v67, v68
	v_add_f32_e32 v66, v66, v67
	v_add_f32_e32 v69, v78, v66
	v_mov_b32_e32 v78, v69
	s_nop 1
	v_permlane16_swap_b32 v69, v78
	v_lshl_add_u64 v[66:67], s[14:15], 0, v[174:175]
	v_lshl_add_u64 v[72:73], v[166:167], 1, v[66:67]
	global_store_dwordx4 v[72:73], v[74:77], off
	v_cvt_pk_bf16_f32 v68, v79, v70
	s_waitcnt lgkmcnt(0)
	v_add_f32_e32 v66, v69, v78
	v_mov_b32_e32 v67, v66
	s_nop 1
	v_permlane32_swap_b32 v66, v67
	v_cvt_pk_bf16_f32 v69, v71, v80
	v_cvt_pk_bf16_f32 v70, v81, v82
	v_cvt_pk_bf16_f32 v71, v83, v84
	global_store_dwordx4 v[72:73], v[68:71], off offset:256
	s_and_saveexec_b64 s[10:11], s[0:1]
	s_cbranch_execz .LBB0_738
	v_lshlrev_b64 v[68:69], 6, v[172:173]
	v_lshl_add_u64 v[68:69], s[12:13], 0, v[68:69]
	v_lshl_add_u64 v[68:69], s[42:43], 2, v[68:69]
	s_lshl_b32 s46, s95, 2
	v_lshl_add_u64 v[68:69], v[68:69], 0, s[46:47]
	s_waitcnt lgkmcnt(0)
	v_add_f32_e32 v66, v66, v67
	global_store_dword v[68:69], v66, off
.LBB0_738:
	s_or_b64 exec, exec, s[10:11]
	v_add_u32_e32 v106, 0x80, v170
	v_ashrrev_i32_e32 v107, 31, v106
	v_lshlrev_b64 v[112:113], 11, v[106:107]
	s_waitcnt lgkmcnt(0)
	v_lshl_add_u64 v[66:67], v[168:169], 0, v[112:113]
	v_mov_b32_e32 v108, v208
	v_mov_b32_e32 v109, v209
	v_mov_b32_e32 v110, v210
	v_mov_b32_e32 v111, v211
	v_mov_b32_e32 v90, v212
	v_mov_b32_e32 v91, v213
	v_mov_b32_e32 v92, v214
	v_mov_b32_e32 v93, v215
	v_add_u32_e32 v102, 0x90, v170
	v_ashrrev_i32_e32 v103, 31, v102
	v_add_u32_e32 v96, 0xa0, v170
	v_lshlrev_b64 v[104:105], 11, v[102:103]
	v_ashrrev_i32_e32 v97, 31, v96
	v_add_u32_e32 v94, 0xb0, v170
	v_lshl_add_u64 v[66:67], v[168:169], 0, v[104:105]
	v_lshlrev_b64 v[100:101], 11, v[96:97]
	v_ashrrev_i32_e32 v95, 31, v94
	v_mov_b32_e32 v86, v216
	v_mov_b32_e32 v87, v217
	v_mov_b32_e32 v88, v218
	v_mov_b32_e32 v89, v219
	v_mov_b32_e32 v82, v220
	v_mov_b32_e32 v83, v221
	v_mov_b32_e32 v84, v222
	v_mov_b32_e32 v85, v223
	v_lshl_add_u64 v[66:67], v[168:169], 0, v[100:101]
	v_lshlrev_b64 v[98:99], 11, v[94:95]
	v_mov_b32_e32 v78, v224
	v_mov_b32_e32 v79, v225
	v_mov_b32_e32 v80, v226
	v_mov_b32_e32 v81, v227
	v_mov_b32_e32 v74, v228
	v_mov_b32_e32 v75, v229
	v_mov_b32_e32 v76, v230
	v_mov_b32_e32 v77, v231
	v_lshl_add_u64 v[66:67], v[168:169], 0, v[98:99]
	v_mov_b32_e32 v70, v232
	v_mov_b32_e32 v71, v233
	v_mov_b32_e32 v72, v234
	v_mov_b32_e32 v73, v235
	s_nop 0
	v_mov_b32_e32 v66, v236
	v_mov_b32_e32 v67, v237
	v_mov_b32_e32 v68, v238
	v_mov_b32_e32 v69, v239
	s_waitcnt lgkmcnt(0)
	v_lshlrev_b32_e32 v115, 16, v109
	v_lshlrev_b32_e32 v114, 16, v108
	v_and_b32_e32 v108, 0xffff0000, v108
	v_fmac_f32_e32 v115, s2, v64
	v_and_b32_e32 v64, 0xffff0000, v109
	v_fmac_f32_e32 v114, s2, v62
	v_fmac_f32_e32 v108, s2, v63
	v_fmac_f32_e32 v64, s2, v65
	v_lshlrev_b32_e32 v65, 16, v110
	v_and_b32_e32 v109, 0xffff0000, v110
	v_lshl_add_u64 v[62:63], s[14:15], 0, v[112:113]
	v_fmac_f32_e32 v65, s2, v58
	v_fmac_f32_e32 v109, s2, v59
	v_lshlrev_b32_e32 v110, 16, v111
	v_and_b32_e32 v111, 0xffff0000, v111
	v_cvt_pk_bf16_f32 v58, v114, v108
	v_cvt_pk_bf16_f32 v59, v115, v64
	v_lshl_add_u64 v[62:63], v[166:167], 1, v[62:63]
	v_fmac_f32_e32 v110, s2, v60
	v_fmac_f32_e32 v111, s2, v61
	v_cvt_pk_bf16_f32 v60, v65, v109
	v_cvt_pk_bf16_f32 v61, v110, v111
	global_store_dwordx4 v[62:63], v[58:61], off
	s_nop 1
	v_mul_f32_e32 v58, v108, v108
	v_mul_f32_e32 v59, v64, v64
	v_fmac_f32_e32 v58, v114, v114
	v_fmac_f32_e32 v59, v115, v115
	v_add_f32_e32 v58, v58, v59
	v_mul_f32_e32 v59, v109, v109
	v_mul_f32_e32 v60, v111, v111
	v_fmac_f32_e32 v59, v65, v65
	v_fmac_f32_e32 v60, v110, v110
	v_add_f32_e32 v59, v59, v60
	v_add_f32_e32 v58, v58, v59
	v_lshlrev_b32_e32 v59, 16, v90
	v_fmac_f32_e32 v59, s2, v54
	v_and_b32_e32 v54, 0xffff0000, v90
	v_fmac_f32_e32 v54, s2, v55
	v_lshlrev_b32_e32 v55, 16, v91
	v_fmac_f32_e32 v55, s2, v56
	v_and_b32_e32 v56, 0xffff0000, v91
	v_fmac_f32_e32 v56, s2, v57
	v_lshlrev_b32_e32 v57, 16, v92
	v_and_b32_e32 v60, 0xffff0000, v92
	v_fmac_f32_e32 v57, s2, v50
	v_fmac_f32_e32 v60, s2, v51
	v_lshlrev_b32_e32 v61, 16, v93
	v_and_b32_e32 v64, 0xffff0000, v93
	v_cvt_pk_bf16_f32 v50, v59, v54
	v_cvt_pk_bf16_f32 v51, v55, v56
	v_fmac_f32_e32 v61, s2, v52
	v_fmac_f32_e32 v64, s2, v53
	v_cvt_pk_bf16_f32 v52, v57, v60
	v_cvt_pk_bf16_f32 v53, v61, v64
	global_store_dwordx4 v[62:63], v[50:53], off offset:256
	s_nop 1
	v_mul_f32_e32 v50, v54, v54
	v_mul_f32_e32 v51, v56, v56
	v_fmac_f32_e32 v50, v59, v59
	v_fmac_f32_e32 v51, v55, v55
	v_add_f32_e32 v50, v50, v51
	v_mul_f32_e32 v51, v60, v60
	v_mul_f32_e32 v52, v64, v64
	v_fmac_f32_e32 v51, v57, v57
	v_fmac_f32_e32 v52, v61, v61
	v_add_f32_e32 v51, v51, v52
	v_add_f32_e32 v50, v50, v51
	v_add_f32_e32 v50, v58, v50
	v_mov_b32_e32 v51, v50
	s_nop 1
	v_permlane16_swap_b32 v50, v51
	s_waitcnt lgkmcnt(0)
	v_add_f32_e32 v50, v50, v51
	v_mov_b32_e32 v51, v50
	s_nop 1
	v_permlane32_swap_b32 v50, v51
	s_and_saveexec_b64 s[10:11], s[0:1]
	s_cbranch_execz .LBB0_740
	v_lshlrev_b64 v[52:53], 6, v[106:107]
	v_lshl_add_u64 v[52:53], s[12:13], 0, v[52:53]
	v_lshl_add_u64 v[52:53], s[42:43], 2, v[52:53]
	s_lshl_b32 s46, s95, 2
	v_lshl_add_u64 v[52:53], v[52:53], 0, s[46:47]
	s_waitcnt lgkmcnt(0)
	v_add_f32_e32 v50, v50, v51
	global_store_dword v[52:53], v50, off
; __device__ __forceinline__ unsigned cvt_pk_bf16(float lo, float hi) { unsigned r; asm volatile("v_cvt_pk_bf16_f32 %0, %1, %2" : "=v"(r) : "v"(lo), "v"(hi)); return r; }
; __device__ __forceinline__ float bf_lo(unsigned w) { return __uint_as_float(w << 16); }
; __device__ __forceinline__ float bf_hi(unsigned w) { return __uint_as_float(w & 0xffff0000u); }
;     __device__ __forceinline__ void operator()(Acc& acc, const Unit& u, int wr, int wc, int fr, int fq, LAS unsigned char*, const LAS float* rst) const {
;     ...
;             for (int m = 0; m < 4; ++m) {
;                 const int row = row0 + ai * 128 + m * 16; const size_t off = (size_t)row * D + col0; float s = 0.f;
; #pragma unroll
;                 for (int bj = 0; bj < 2; ++bj) { const f32x4 a0 = acc[ai][bj][m][0], a1 = acc[ai][bj][m][1]; const u32x4 o = xo[m][bj];
;                     const float n0 = bf_lo(o.x) + a0[0] * scale, n1 = bf_hi(o.x) + a0[1] * scale, n2 = bf_lo(o.y) + a0[2] * scale, n3 = bf_hi(o.y) + a0[3] * scale;
;                     const float n4 = bf_lo(o.z) + a1[0] * scale, n5 = bf_hi(o.z) + a1[1] * scale, n6 = bf_lo(o.w) + a1[2] * scale, n7 = bf_hi(o.w) + a1[3] * scale;
;                     u32x4 w; w.x = cvt_pk_bf16(n0, n1); w.y = cvt_pk_bf16(n2, n3); w.z = cvt_pk_bf16(n4, n5); w.w = cvt_pk_bf16(n6, n7); *(u32x4*)(XB + off + bj * 128) = w;
;                     s += ((n0 * n0 + n1 * n1) + (n2 * n2 + n3 * n3)) + ((n4 * n4 + n5 * n5) + (n6 * n6 + n7 * n7)); }
;                 s += __shfl_xor(s, 16); s += __shfl_xor(s, 32);
;                 if (fq == 0) ssq[(size_t)row * 16 + u.pn * 4 + wc] = s;
.LBB0_740:
	s_or_b64 exec, exec, s[10:11]
	v_lshlrev_b32_e32 v50, 16, v86
	v_fmac_f32_e32 v50, s2, v46
	v_and_b32_e32 v46, 0xffff0000, v86
	v_fmac_f32_e32 v46, s2, v47
	v_lshlrev_b32_e32 v47, 16, v87
	v_fmac_f32_e32 v47, s2, v48
	v_and_b32_e32 v48, 0xffff0000, v87
	v_fmac_f32_e32 v48, s2, v49
	v_lshlrev_b32_e32 v49, 16, v88
	s_waitcnt lgkmcnt(0)
	v_and_b32_e32 v51, 0xffff0000, v88
	v_fmac_f32_e32 v49, s2, v42
	v_fmac_f32_e32 v51, s2, v43
	v_and_b32_e32 v53, 0xffff0000, v89
	v_cvt_pk_bf16_f32 v42, v50, v46
	v_cvt_pk_bf16_f32 v43, v47, v48
	v_mul_f32_e32 v46, v46, v46
	v_mul_f32_e32 v48, v48, v48
	v_lshlrev_b32_e32 v52, 16, v89
	v_fmac_f32_e32 v53, s2, v45
	v_fmac_f32_e32 v46, v50, v50
	v_fmac_f32_e32 v48, v47, v47
	v_fmac_f32_e32 v52, s2, v44
	v_add_f32_e32 v46, v46, v48
	v_mul_f32_e32 v47, v51, v51
	v_mul_f32_e32 v48, v53, v53
	v_fmac_f32_e32 v47, v49, v49
	v_fmac_f32_e32 v48, v52, v52
	v_add_f32_e32 v47, v47, v48
	v_add_f32_e32 v46, v46, v47
	v_lshlrev_b32_e32 v47, 16, v82
	v_fmac_f32_e32 v47, s2, v38
	v_and_b32_e32 v38, 0xffff0000, v82
	v_and_b32_e32 v48, 0xffff0000, v83
	v_cvt_pk_bf16_f32 v44, v49, v51
	v_fmac_f32_e32 v38, s2, v39
	v_lshlrev_b32_e32 v39, 16, v83
	v_fmac_f32_e32 v48, s2, v41
	v_lshlrev_b32_e32 v49, 16, v84
	v_and_b32_e32 v50, 0xffff0000, v84
	v_cvt_pk_bf16_f32 v45, v52, v53
	v_fmac_f32_e32 v39, s2, v40
	v_fmac_f32_e32 v49, s2, v34
	v_fmac_f32_e32 v50, s2, v35
	v_and_b32_e32 v52, 0xffff0000, v85
	v_mul_f32_e32 v34, v38, v38
	v_mul_f32_e32 v35, v48, v48
	v_lshlrev_b32_e32 v51, 16, v85
	v_fmac_f32_e32 v52, s2, v37
	v_fmac_f32_e32 v34, v47, v47
	v_fmac_f32_e32 v35, v39, v39
	v_fmac_f32_e32 v51, s2, v36
	v_add_f32_e32 v34, v34, v35
	v_mul_f32_e32 v35, v50, v50
	v_mul_f32_e32 v36, v52, v52
	v_fmac_f32_e32 v35, v49, v49
	v_fmac_f32_e32 v36, v51, v51
	v_add_f32_e32 v35, v35, v36
	v_add_f32_e32 v34, v34, v35
	v_add_f32_e32 v37, v46, v34
	v_mov_b32_e32 v46, v37
	s_nop 1
	v_permlane16_swap_b32 v37, v46
	v_lshl_add_u64 v[34:35], s[14:15], 0, v[104:105]
	v_lshl_add_u64 v[40:41], v[166:167], 1, v[34:35]
	global_store_dwordx4 v[40:41], v[42:45], off
	v_cvt_pk_bf16_f32 v36, v47, v38
	s_waitcnt lgkmcnt(0)
	v_add_f32_e32 v34, v37, v46
	v_mov_b32_e32 v35, v34
	s_nop 1
	v_permlane32_swap_b32 v34, v35
	v_cvt_pk_bf16_f32 v37, v39, v48
	v_cvt_pk_bf16_f32 v38, v49, v50
	v_cvt_pk_bf16_f32 v39, v51, v52
	global_store_dwordx4 v[40:41], v[36:39], off offset:256
	s_and_saveexec_b64 s[10:11], s[0:1]
	s_cbranch_execz .LBB0_742
	v_lshlrev_b64 v[36:37], 6, v[102:103]
	v_lshl_add_u64 v[36:37], s[12:13], 0, v[36:37]
	v_lshl_add_u64 v[36:37], s[42:43], 2, v[36:37]
	s_lshl_b32 s46, s95, 2
	v_lshl_add_u64 v[36:37], v[36:37], 0, s[46:47]
	s_waitcnt lgkmcnt(0)
	v_add_f32_e32 v34, v34, v35
	global_store_dword v[36:37], v34, off
; __device__ __forceinline__ unsigned cvt_pk_bf16(float lo, float hi) { unsigned r; asm volatile("v_cvt_pk_bf16_f32 %0, %1, %2" : "=v"(r) : "v"(lo), "v"(hi)); return r; }
; __device__ __forceinline__ float bf_lo(unsigned w) { return __uint_as_float(w << 16); }
; __device__ __forceinline__ float bf_hi(unsigned w) { return __uint_as_float(w & 0xffff0000u); }
;     __device__ __forceinline__ void operator()(Acc& acc, const Unit& u, int wr, int wc, int fr, int fq, LAS unsigned char*, const LAS float* rst) const {
;     ...
;             for (int m = 0; m < 4; ++m) {
;                 const int row = row0 + ai * 128 + m * 16; const size_t off = (size_t)row * D + col0; float s = 0.f;
; #pragma unroll
;                 for (int bj = 0; bj < 2; ++bj) { const f32x4 a0 = acc[ai][bj][m][0], a1 = acc[ai][bj][m][1]; const u32x4 o = xo[m][bj];
;                     const float n0 = bf_lo(o.x) + a0[0] * scale, n1 = bf_hi(o.x) + a0[1] * scale, n2 = bf_lo(o.y) + a0[2] * scale, n3 = bf_hi(o.y) + a0[3] * scale;
;                     const float n4 = bf_lo(o.z) + a1[0] * scale, n5 = bf_hi(o.z) + a1[1] * scale, n6 = bf_lo(o.w) + a1[2] * scale, n7 = bf_hi(o.w) + a1[3] * scale;
;                     u32x4 w; w.x = cvt_pk_bf16(n0, n1); w.y = cvt_pk_bf16(n2, n3); w.z = cvt_pk_bf16(n4, n5); w.w = cvt_pk_bf16(n6, n7); *(u32x4*)(XB + off + bj * 128) = w;
;                     s += ((n0 * n0 + n1 * n1) + (n2 * n2 + n3 * n3)) + ((n4 * n4 + n5 * n5) + (n6 * n6 + n7 * n7)); }
;                 s += __shfl_xor(s, 16); s += __shfl_xor(s, 32);
;                 if (fq == 0) ssq[(size_t)row * 16 + u.pn * 4 + wc] = s;
;             }
.LBB0_742:
	s_or_b64 exec, exec, s[10:11]
	v_lshlrev_b32_e32 v34, 16, v78
	v_fmac_f32_e32 v34, s2, v30
	v_and_b32_e32 v30, 0xffff0000, v78
	v_fmac_f32_e32 v30, s2, v31
	v_lshlrev_b32_e32 v31, 16, v79
	v_fmac_f32_e32 v31, s2, v32
	v_and_b32_e32 v32, 0xffff0000, v79
	v_fmac_f32_e32 v32, s2, v33
	v_lshlrev_b32_e32 v33, 16, v80
	s_waitcnt lgkmcnt(0)
	v_and_b32_e32 v35, 0xffff0000, v80
	v_fmac_f32_e32 v33, s2, v26
	v_fmac_f32_e32 v35, s2, v27
	v_and_b32_e32 v37, 0xffff0000, v81
	v_cvt_pk_bf16_f32 v26, v34, v30
	v_cvt_pk_bf16_f32 v27, v31, v32
	v_mul_f32_e32 v30, v30, v30
	v_mul_f32_e32 v32, v32, v32
	v_lshlrev_b32_e32 v36, 16, v81
	v_fmac_f32_e32 v37, s2, v29
	v_fmac_f32_e32 v30, v34, v34
	v_fmac_f32_e32 v32, v31, v31
	v_fmac_f32_e32 v36, s2, v28
	v_add_f32_e32 v30, v30, v32
	v_mul_f32_e32 v31, v35, v35
	v_mul_f32_e32 v32, v37, v37
	v_fmac_f32_e32 v31, v33, v33
	v_fmac_f32_e32 v32, v36, v36
	v_add_f32_e32 v31, v31, v32
	v_add_f32_e32 v30, v30, v31
	v_lshlrev_b32_e32 v31, 16, v74
	v_fmac_f32_e32 v31, s2, v22
	v_and_b32_e32 v22, 0xffff0000, v74
	v_and_b32_e32 v32, 0xffff0000, v75
	v_cvt_pk_bf16_f32 v28, v33, v35
	v_fmac_f32_e32 v22, s2, v23
	v_lshlrev_b32_e32 v23, 16, v75
	v_fmac_f32_e32 v32, s2, v25
	v_lshlrev_b32_e32 v33, 16, v76
	v_and_b32_e32 v34, 0xffff0000, v76
	v_cvt_pk_bf16_f32 v29, v36, v37
	v_fmac_f32_e32 v23, s2, v24
	v_fmac_f32_e32 v33, s2, v18
	v_fmac_f32_e32 v34, s2, v19
	v_and_b32_e32 v36, 0xffff0000, v77
	v_mul_f32_e32 v18, v22, v22
	v_mul_f32_e32 v19, v32, v32
	v_lshlrev_b32_e32 v35, 16, v77
	v_fmac_f32_e32 v36, s2, v21
	v_fmac_f32_e32 v18, v31, v31
	v_fmac_f32_e32 v19, v23, v23
	v_fmac_f32_e32 v35, s2, v20
	v_add_f32_e32 v18, v18, v19
	v_mul_f32_e32 v19, v34, v34
	v_mul_f32_e32 v20, v36, v36
	v_fmac_f32_e32 v19, v33, v33
	v_fmac_f32_e32 v20, v35, v35
	v_add_f32_e32 v19, v19, v20
	v_add_f32_e32 v18, v18, v19
	v_add_f32_e32 v21, v30, v18
	v_mov_b32_e32 v30, v21
	s_nop 1
	v_permlane16_swap_b32 v21, v30
	v_lshl_add_u64 v[18:19], s[14:15], 0, v[100:101]
	v_lshl_add_u64 v[24:25], v[166:167], 1, v[18:19]
	global_store_dwordx4 v[24:25], v[26:29], off
	v_cvt_pk_bf16_f32 v20, v31, v22
	s_waitcnt lgkmcnt(0)
	v_add_f32_e32 v18, v21, v30
	v_mov_b32_e32 v19, v18
	s_nop 1
	v_permlane32_swap_b32 v18, v19
	v_cvt_pk_bf16_f32 v21, v23, v32
	v_cvt_pk_bf16_f32 v22, v33, v34
	v_cvt_pk_bf16_f32 v23, v35, v36
	global_store_dwordx4 v[24:25], v[20:23], off offset:256
	s_and_saveexec_b64 s[10:11], s[0:1]
	s_cbranch_execz .LBB0_744
	v_lshlrev_b64 v[20:21], 6, v[96:97]
	v_lshl_add_u64 v[20:21], s[12:13], 0, v[20:21]
	v_lshl_add_u64 v[20:21], s[42:43], 2, v[20:21]
	s_lshl_b32 s46, s95, 2
	v_lshl_add_u64 v[20:21], v[20:21], 0, s[46:47]
	s_waitcnt lgkmcnt(0)
	v_add_f32_e32 v18, v18, v19
	global_store_dword v[20:21], v18, off
.LBB0_744:
	s_or_b64 exec, exec, s[10:11]
	v_lshlrev_b32_e32 v20, 16, v71
	v_lshlrev_b32_e32 v18, 16, v70
	s_waitcnt lgkmcnt(0)
	v_and_b32_e32 v19, 0xffff0000, v70
	v_fmac_f32_e32 v20, s2, v16
	v_and_b32_e32 v16, 0xffff0000, v71
	v_fmac_f32_e32 v18, s2, v14
	v_fmac_f32_e32 v19, s2, v15
	v_fmac_f32_e32 v16, s2, v17
	v_lshlrev_b32_e32 v17, 16, v72
	v_and_b32_e32 v21, 0xffff0000, v72
	v_lshl_add_u64 v[14:15], s[14:15], 0, v[98:99]
	v_fmac_f32_e32 v17, s2, v10
	v_fmac_f32_e32 v21, s2, v11
	v_lshlrev_b32_e32 v22, 16, v73
	v_and_b32_e32 v23, 0xffff0000, v73
	v_cvt_pk_bf16_f32 v10, v18, v19
	v_cvt_pk_bf16_f32 v11, v20, v16
	v_lshl_add_u64 v[14:15], v[166:167], 1, v[14:15]
	v_fmac_f32_e32 v22, s2, v12
	v_fmac_f32_e32 v23, s2, v13
	v_cvt_pk_bf16_f32 v12, v17, v21
	v_cvt_pk_bf16_f32 v13, v22, v23
	global_store_dwordx4 v[14:15], v[10:13], off
	s_nop 1
	v_mul_f32_e32 v10, v19, v19
	v_mul_f32_e32 v11, v16, v16
	v_fmac_f32_e32 v10, v18, v18
	v_fmac_f32_e32 v11, v20, v20
	v_add_f32_e32 v10, v10, v11
	v_mul_f32_e32 v11, v21, v21
	v_mul_f32_e32 v12, v23, v23
	v_fmac_f32_e32 v11, v17, v17
	v_fmac_f32_e32 v12, v22, v22
	v_add_f32_e32 v11, v11, v12
	v_add_f32_e32 v10, v10, v11
	v_lshlrev_b32_e32 v11, 16, v66
	v_fmac_f32_e32 v11, s2, v6
	v_and_b32_e32 v6, 0xffff0000, v66
	v_fmac_f32_e32 v6, s2, v7
	v_lshlrev_b32_e32 v7, 16, v67
	v_fmac_f32_e32 v7, s2, v8
	v_and_b32_e32 v8, 0xffff0000, v67
	v_fmac_f32_e32 v8, s2, v9
	v_lshlrev_b32_e32 v9, 16, v68
	v_and_b32_e32 v12, 0xffff0000, v68
	v_fmac_f32_e32 v9, s2, v2
	v_fmac_f32_e32 v12, s2, v3
	v_lshlrev_b32_e32 v13, 16, v69
	v_and_b32_e32 v16, 0xffff0000, v69
	v_cvt_pk_bf16_f32 v2, v11, v6
	v_cvt_pk_bf16_f32 v3, v7, v8
	v_fmac_f32_e32 v13, s2, v4
	v_fmac_f32_e32 v16, s2, v5
	v_cvt_pk_bf16_f32 v4, v9, v12
	v_cvt_pk_bf16_f32 v5, v13, v16
	global_store_dwordx4 v[14:15], v[2:5], off offset:256
	s_nop 1
	v_mul_f32_e32 v2, v6, v6
	v_mul_f32_e32 v3, v8, v8
	v_fmac_f32_e32 v2, v11, v11
	v_fmac_f32_e32 v3, v7, v7
	v_add_f32_e32 v2, v2, v3
	v_mul_f32_e32 v3, v12, v12
	v_mul_f32_e32 v4, v16, v16
	v_fmac_f32_e32 v3, v9, v9
	v_fmac_f32_e32 v4, v13, v13
	v_add_f32_e32 v3, v3, v4
	v_add_f32_e32 v2, v2, v3
	v_add_f32_e32 v2, v10, v2
	v_mov_b32_e32 v3, v2
	s_nop 1
	v_permlane16_swap_b32 v2, v3
	s_waitcnt lgkmcnt(0)
	v_add_f32_e32 v2, v2, v3
	v_mov_b32_e32 v3, v2
	s_nop 1
	v_permlane32_swap_b32 v2, v3
	s_and_saveexec_b64 s[10:11], s[0:1]
	s_cbranch_execz .LBB0_746
	v_lshlrev_b64 v[4:5], 6, v[94:95]
	v_lshl_add_u64 v[4:5], s[12:13], 0, v[4:5]
	v_lshl_add_u64 v[4:5], s[42:43], 2, v[4:5]
	s_lshl_b32 s46, s95, 2
	v_lshl_add_u64 v[4:5], v[4:5], 0, s[46:47]
	s_waitcnt lgkmcnt(0)
	v_add_f32_e32 v2, v2, v3
	global_store_dword v[4:5], v2, off
